# tail transposer v2: Mamba in/out-proj + layer-0 ffn_down weights converted by idle WGs in phase 7 tail; layer-1 ffn_down + PLE weights in phase 19 tail
# speedup vs baseline: 1.0232x; 1.0087x over previous
; #define LAS __attribute__((address_space(3)))
; __device__ __forceinline__ unsigned cvt_pk_bf16(float lo, float hi) { unsigned r; asm volatile("v_cvt_pk_bf16_f32 %0, %1, %2" : "=v"(r) : "v"(lo), "v"(hi)); return r; }
; __device__ __forceinline__ void xpose_item(const float* src, int ld, bf16_t* dst, int K, int k0, LAS float* scr, int lane, const float* gk) {
;     if (src) {
; #pragma unroll 8
;         for (int i = 0; i < 32; ++i) { const int kk = 2 * i + (lane >> 5); scr[kk * 33 + (lane & 31)] = __builtin_nontemporal_load(src + (size_t)(k0 + kk) * ld + (lane & 31)); }
;     } else {
; #pragma unroll 8
;         for (int i = 0; i < 32; ++i) { const int kk = 2 * i + (lane >> 5); scr[kk * 33 + (lane & 31)] = 0.f; }
;     }
;     const int c = lane & 7;
;     f32x4 g0 = (f32x4){1.f, 1.f, 1.f, 1.f}, g1 = g0;
;     if (gk) { g0 = *(const f32x4*)(gk + k0 + 8 * c); g1 = *(const f32x4*)(gk + k0 + 8 * c + 4); }
;     asm volatile("s_waitcnt lgkmcnt(0)" ::: "memory");
; #pragma unroll
;     for (int j = 0; j < 4; ++j) { const int n = (lane >> 3) + 8 * j; const LAS float* s = scr + (8 * c) * 33 + n;
;         u32x4 o; o.x = cvt_pk_bf16(s[0 * 33] * g0[0], s[1 * 33] * g0[1]); o.y = cvt_pk_bf16(s[2 * 33] * g0[2], s[3 * 33] * g0[3]); o.z = cvt_pk_bf16(s[4 * 33] * g1[0], s[5 * 33] * g1[1]); o.w = cvt_pk_bf16(s[6 * 33] * g1[2], s[7 * 33] * g1[3]);
;         *(u32x4*)(dst + (size_t)n * K + k0 + 8 * c) = o; }
;     asm volatile("s_waitcnt lgkmcnt(0)" ::: "memory");
; }
; __global__ void __launch_bounds__(512) mega(Args a_byval) {
;     ...
;             it = xpose_all(a.in[25] + (size_t)lyr * D * DFF, nullptr, 2048, DFF, 2048, 2048, 0, (bf16_t*)(ws + (lyr ? WS_W_D : WS_W_D0)), it, NGW, scr, lane);
.LBB0_418:
	s_waitcnt vmcnt(0)
	s_barrier
	s_cmp_lg_u32 s76, 7
	s_cbranch_scc1 .Lxt7_done
	v_readlane_b32 s59, v255, 5
	s_cmpk_lg_i32 s59, 0x100
	s_cbranch_scc1 .Lxt7_done
	s_cmpk_lt_i32 s94, 0x80
	s_cbranch_scc1 .Lxt7_done
	s_sub_i32 s59, s94, 0x80
	s_lshl_b32 s59, s59, 3
	s_add_i32 s59, s59, s95
	s_mul_i32 s64, s95, 0x2100
	v_and_b32_e32 v2, 31, v200
	v_lshrrev_b32_e32 v3, 5, v200
	v_lshlrev_b32_e32 v4, 2, v2
	v_mul_u32_u24_e32 v6, 0x84, v3
	v_add3_u32 v6, v6, v4, s64
	v_and_b32_e32 v7, 7, v200
	v_lshrrev_b32_e32 v8, 3, v200
	v_mul_u32_u24_e32 v9, 0x420, v7
	v_lshl_add_u32 v9, v8, 2, v9
	v_add_u32_e32 v9, s64, v9
	s_cmpk_ge_i32 s59, 0x1600
	s_cbranch_scc1 .Lxpf0_end
	s_load_dwordx2 s[60:61], s[92:93], 0xc8
	s_load_dwordx2 s[62:63], s[92:93], 0xe8
	v_mov_b32_e32 v5, 0x2000
	v_mul_u32_u24_e32 v5, v3, v5
	v_add_u32_e32 v5, v5, v4
	v_mov_b32_e32 v10, 0x2c00
	v_mul_u32_u24_e32 v10, v8, v10
	v_lshl_add_u32 v12, v7, 4, v10
	v_add_u32_e32 v13, 0x16000, v12
	v_add_u32_e32 v14, 0x2c000, v12
	v_add_u32_e32 v15, 0x42000, v12
	s_waitcnt lgkmcnt(0)
	s_add_u32 s62, s62, 0x1f800000
	s_addc_u32 s63, s63, 0
	s_lshr_b32 s64, s59, 6
	s_and_b32 s65, s59, 63
	s_mul_i32 s66, s64, 0x80000
	s_lshl_b32 s67, s65, 7
	s_add_i32 s66, s66, s67
	s_add_u32 s66, s60, s66
	s_addc_u32 s67, s61, 0
	v_mov_b32_e32 v11, v5
	global_load_dword v20, v11, s[66:67] nt
	v_add_u32_e32 v11, 0x4000, v11
	global_load_dword v21, v11, s[66:67] nt
	v_add_u32_e32 v11, 0x4000, v11
	global_load_dword v22, v11, s[66:67] nt
	v_add_u32_e32 v11, 0x4000, v11
	global_load_dword v23, v11, s[66:67] nt
	v_add_u32_e32 v11, 0x4000, v11
	global_load_dword v24, v11, s[66:67] nt
	v_add_u32_e32 v11, 0x4000, v11
	global_load_dword v25, v11, s[66:67] nt
	v_add_u32_e32 v11, 0x4000, v11
	global_load_dword v26, v11, s[66:67] nt
	v_add_u32_e32 v11, 0x4000, v11
	global_load_dword v27, v11, s[66:67] nt
	v_add_u32_e32 v11, 0x4000, v11
	global_load_dword v28, v11, s[66:67] nt
	v_add_u32_e32 v11, 0x4000, v11
	global_load_dword v29, v11, s[66:67] nt
	v_add_u32_e32 v11, 0x4000, v11
	global_load_dword v30, v11, s[66:67] nt
	v_add_u32_e32 v11, 0x4000, v11
	global_load_dword v31, v11, s[66:67] nt
	v_add_u32_e32 v11, 0x4000, v11
	global_load_dword v32, v11, s[66:67] nt
	v_add_u32_e32 v11, 0x4000, v11
	global_load_dword v33, v11, s[66:67] nt
	v_add_u32_e32 v11, 0x4000, v11
	global_load_dword v34, v11, s[66:67] nt
	v_add_u32_e32 v11, 0x4000, v11
	global_load_dword v35, v11, s[66:67] nt
	v_add_u32_e32 v11, 0x4000, v11
	global_load_dword v36, v11, s[66:67] nt
	v_add_u32_e32 v11, 0x4000, v11
	global_load_dword v37, v11, s[66:67] nt
	v_add_u32_e32 v11, 0x4000, v11
	global_load_dword v38, v11, s[66:67] nt
	v_add_u32_e32 v11, 0x4000, v11
	global_load_dword v39, v11, s[66:67] nt
	v_add_u32_e32 v11, 0x4000, v11
	global_load_dword v40, v11, s[66:67] nt
	v_add_u32_e32 v11, 0x4000, v11
	global_load_dword v41, v11, s[66:67] nt
	v_add_u32_e32 v11, 0x4000, v11
	global_load_dword v42, v11, s[66:67] nt
	v_add_u32_e32 v11, 0x4000, v11
	global_load_dword v43, v11, s[66:67] nt
	v_add_u32_e32 v11, 0x4000, v11
	global_load_dword v44, v11, s[66:67] nt
	v_add_u32_e32 v11, 0x4000, v11
	global_load_dword v45, v11, s[66:67] nt
	v_add_u32_e32 v11, 0x4000, v11
	global_load_dword v46, v11, s[66:67] nt
	v_add_u32_e32 v11, 0x4000, v11
	global_load_dword v47, v11, s[66:67] nt
	v_add_u32_e32 v11, 0x4000, v11
	global_load_dword v48, v11, s[66:67] nt
	v_add_u32_e32 v11, 0x4000, v11
	global_load_dword v49, v11, s[66:67] nt
	v_add_u32_e32 v11, 0x4000, v11
	global_load_dword v50, v11, s[66:67] nt
	v_add_u32_e32 v11, 0x4000, v11
	global_load_dword v51, v11, s[66:67] nt
.Lxpf0_loop:
	s_add_i32 s32, s59, 0x400
	s_cmpk_lt_i32 s32, 0x1600
	s_cbranch_scc0 .Lxpf0_dumB
	s_lshr_b32 s64, s32, 6
	s_and_b32 s65, s32, 63
	s_mul_i32 s66, s64, 0x80000
	s_lshl_b32 s67, s65, 7
	s_add_i32 s66, s66, s67
	s_add_u32 s66, s60, s66
	s_addc_u32 s67, s61, 0
	v_mov_b32_e32 v11, v5
	global_load_dword v108, v11, s[66:67] nt
	v_add_u32_e32 v11, 0x4000, v11
	global_load_dword v109, v11, s[66:67] nt
	v_add_u32_e32 v11, 0x4000, v11
	global_load_dword v110, v11, s[66:67] nt
	v_add_u32_e32 v11, 0x4000, v11
	global_load_dword v111, v11, s[66:67] nt
	v_add_u32_e32 v11, 0x4000, v11
	global_load_dword v112, v11, s[66:67] nt
	v_add_u32_e32 v11, 0x4000, v11
	global_load_dword v113, v11, s[66:67] nt
	v_add_u32_e32 v11, 0x4000, v11
	global_load_dword v114, v11, s[66:67] nt
	v_add_u32_e32 v11, 0x4000, v11
	global_load_dword v115, v11, s[66:67] nt
	v_add_u32_e32 v11, 0x4000, v11
	global_load_dword v116, v11, s[66:67] nt
	v_add_u32_e32 v11, 0x4000, v11
	global_load_dword v117, v11, s[66:67] nt
	v_add_u32_e32 v11, 0x4000, v11
	global_load_dword v118, v11, s[66:67] nt
	v_add_u32_e32 v11, 0x4000, v11
	global_load_dword v119, v11, s[66:67] nt
	v_add_u32_e32 v11, 0x4000, v11
	global_load_dword v120, v11, s[66:67] nt
	v_add_u32_e32 v11, 0x4000, v11
	global_load_dword v121, v11, s[66:67] nt
	v_add_u32_e32 v11, 0x4000, v11
	global_load_dword v122, v11, s[66:67] nt
	v_add_u32_e32 v11, 0x4000, v11
	global_load_dword v123, v11, s[66:67] nt
	v_add_u32_e32 v11, 0x4000, v11
	global_load_dword v124, v11, s[66:67] nt
	v_add_u32_e32 v11, 0x4000, v11
	global_load_dword v125, v11, s[66:67] nt
	v_add_u32_e32 v11, 0x4000, v11
	global_load_dword v126, v11, s[66:67] nt
	v_add_u32_e32 v11, 0x4000, v11
	global_load_dword v127, v11, s[66:67] nt
	v_add_u32_e32 v11, 0x4000, v11
	global_load_dword v128, v11, s[66:67] nt
	v_add_u32_e32 v11, 0x4000, v11
	global_load_dword v129, v11, s[66:67] nt
	v_add_u32_e32 v11, 0x4000, v11
	global_load_dword v130, v11, s[66:67] nt
	v_add_u32_e32 v11, 0x4000, v11
	global_load_dword v131, v11, s[66:67] nt
	v_add_u32_e32 v11, 0x4000, v11
	global_load_dword v132, v11, s[66:67] nt
	v_add_u32_e32 v11, 0x4000, v11
	global_load_dword v133, v11, s[66:67] nt
	v_add_u32_e32 v11, 0x4000, v11
	global_load_dword v134, v11, s[66:67] nt
	v_add_u32_e32 v11, 0x4000, v11
	global_load_dword v135, v11, s[66:67] nt
	v_add_u32_e32 v11, 0x4000, v11
	global_load_dword v136, v11, s[66:67] nt
	v_add_u32_e32 v11, 0x4000, v11
	global_load_dword v137, v11, s[66:67] nt
	v_add_u32_e32 v11, 0x4000, v11
	global_load_dword v138, v11, s[66:67] nt
	v_add_u32_e32 v11, 0x4000, v11
	global_load_dword v139, v11, s[66:67] nt
	s_branch .Lxpf0_procA

; #define LAS __attribute__((address_space(3)))
; __device__ __forceinline__ unsigned cvt_pk_bf16(float lo, float hi) { unsigned r; asm volatile("v_cvt_pk_bf16_f32 %0, %1, %2" : "=v"(r) : "v"(lo), "v"(hi)); return r; }
; __device__ __forceinline__ void xpose_item(const float* src, int ld, bf16_t* dst, int K, int k0, LAS float* scr, int lane, const float* gk) {
;     if (src) {
; #pragma unroll 8
;         for (int i = 0; i < 32; ++i) { const int kk = 2 * i + (lane >> 5); scr[kk * 33 + (lane & 31)] = __builtin_nontemporal_load(src + (size_t)(k0 + kk) * ld + (lane & 31)); }
;     } else {
; #pragma unroll 8
;         for (int i = 0; i < 32; ++i) { const int kk = 2 * i + (lane >> 5); scr[kk * 33 + (lane & 31)] = 0.f; }
;     }
;     const int c = lane & 7;
;     f32x4 g0 = (f32x4){1.f, 1.f, 1.f, 1.f}, g1 = g0;
;     if (gk) { g0 = *(const f32x4*)(gk + k0 + 8 * c); g1 = *(const f32x4*)(gk + k0 + 8 * c + 4); }
;     asm volatile("s_waitcnt lgkmcnt(0)" ::: "memory");
; #pragma unroll
;     for (int j = 0; j < 4; ++j) { const int n = (lane >> 3) + 8 * j; const LAS float* s = scr + (8 * c) * 33 + n;
;         u32x4 o; o.x = cvt_pk_bf16(s[0 * 33] * g0[0], s[1 * 33] * g0[1]); o.y = cvt_pk_bf16(s[2 * 33] * g0[2], s[3 * 33] * g0[3]); o.z = cvt_pk_bf16(s[4 * 33] * g1[0], s[5 * 33] * g1[1]); o.w = cvt_pk_bf16(s[6 * 33] * g1[2], s[7 * 33] * g1[3]);
;         *(u32x4*)(dst + (size_t)n * K + k0 + 8 * c) = o; }
;     asm volatile("s_waitcnt lgkmcnt(0)" ::: "memory");
; }
; __global__ void __launch_bounds__(512) mega(Args a_byval) {
;     ...
;             it = xpose_all(a.in[25] + (size_t)lyr * D * DFF, nullptr, 2048, DFF, 2048, 2048, 0, (bf16_t*)(ws + (lyr ? WS_W_D : WS_W_D0)), it, NGW, scr, lane);
.Lxpf0_procA:
	s_lshr_b32 s64, s59, 6
	s_and_b32 s65, s59, 63
	s_mul_i32 s68, s65, 0x58000
	s_lshl_b32 s64, s64, 7
	s_add_i32 s68, s68, s64
	s_add_u32 s64, s62, s68
	s_addc_u32 s65, s63, 0
	s_waitcnt vmcnt(63)
	ds_write_b32 v6, v20 offset:0
	s_waitcnt vmcnt(62)
	ds_write_b32 v6, v21 offset:264
	s_waitcnt vmcnt(61)
	ds_write_b32 v6, v22 offset:528
	s_waitcnt vmcnt(60)
	ds_write_b32 v6, v23 offset:792
	s_waitcnt vmcnt(59)
	ds_write_b32 v6, v24 offset:1056
	s_waitcnt vmcnt(58)
	ds_write_b32 v6, v25 offset:1320
	s_waitcnt vmcnt(57)
	ds_write_b32 v6, v26 offset:1584
	s_waitcnt vmcnt(56)
	ds_write_b32 v6, v27 offset:1848
	s_waitcnt vmcnt(55)
	ds_write_b32 v6, v28 offset:2112
	s_waitcnt vmcnt(54)
	ds_write_b32 v6, v29 offset:2376
	s_waitcnt vmcnt(53)
	ds_write_b32 v6, v30 offset:2640
	s_waitcnt vmcnt(52)
	ds_write_b32 v6, v31 offset:2904
	s_waitcnt vmcnt(51)
	ds_write_b32 v6, v32 offset:3168
	s_waitcnt vmcnt(50)
	ds_write_b32 v6, v33 offset:3432
	s_waitcnt vmcnt(49)
	ds_write_b32 v6, v34 offset:3696
	s_waitcnt vmcnt(48)
	ds_write_b32 v6, v35 offset:3960
	s_waitcnt vmcnt(47)
	ds_write_b32 v6, v36 offset:4224
	s_waitcnt vmcnt(46)
	ds_write_b32 v6, v37 offset:4488
	s_waitcnt vmcnt(45)
	ds_write_b32 v6, v38 offset:4752
	s_waitcnt vmcnt(44)
	ds_write_b32 v6, v39 offset:5016
	s_waitcnt vmcnt(43)
	ds_write_b32 v6, v40 offset:5280
	s_waitcnt vmcnt(42)
	ds_write_b32 v6, v41 offset:5544
	s_waitcnt vmcnt(41)
	ds_write_b32 v6, v42 offset:5808
	s_waitcnt vmcnt(40)
	ds_write_b32 v6, v43 offset:6072
	s_waitcnt vmcnt(39)
	ds_write_b32 v6, v44 offset:6336
	s_waitcnt vmcnt(38)
	ds_write_b32 v6, v45 offset:6600
	s_waitcnt vmcnt(37)
	ds_write_b32 v6, v46 offset:6864
	s_waitcnt vmcnt(36)
	ds_write_b32 v6, v47 offset:7128
	s_waitcnt vmcnt(35)
	ds_write_b32 v6, v48 offset:7392
	s_waitcnt vmcnt(34)
	ds_write_b32 v6, v49 offset:7656
	s_waitcnt vmcnt(33)
	ds_write_b32 v6, v50 offset:7920
	s_waitcnt vmcnt(32)
	ds_write_b32 v6, v51 offset:8184
	s_waitcnt lgkmcnt(0)
	ds_read2_b32 v[60:61], v9 offset0:0 offset1:33
	ds_read2_b32 v[62:63], v9 offset0:66 offset1:99
	ds_read2_b32 v[64:65], v9 offset0:132 offset1:165
	ds_read2_b32 v[66:67], v9 offset0:198 offset1:231
	ds_read2_b32 v[68:69], v9 offset0:8 offset1:41
	ds_read2_b32 v[70:71], v9 offset0:74 offset1:107
	ds_read2_b32 v[72:73], v9 offset0:140 offset1:173
	ds_read2_b32 v[74:75], v9 offset0:206 offset1:239
	ds_read2_b32 v[76:77], v9 offset0:16 offset1:49
	ds_read2_b32 v[78:79], v9 offset0:82 offset1:115
	ds_read2_b32 v[80:81], v9 offset0:148 offset1:181
	ds_read2_b32 v[82:83], v9 offset0:214 offset1:247
	ds_read2_b32 v[84:85], v9 offset0:24 offset1:57
	ds_read2_b32 v[86:87], v9 offset0:90 offset1:123
	ds_read2_b32 v[88:89], v9 offset0:156 offset1:189
	ds_read2_b32 v[90:91], v9 offset0:222 offset1:255
	s_waitcnt lgkmcnt(12)
	v_cvt_pk_bf16_f32 v92, v60, v61
	v_cvt_pk_bf16_f32 v93, v62, v63
	v_cvt_pk_bf16_f32 v94, v64, v65
	v_cvt_pk_bf16_f32 v95, v66, v67
	global_store_dwordx4 v12, v[92:95], s[64:65]
	s_waitcnt lgkmcnt(8)
	v_cvt_pk_bf16_f32 v96, v68, v69
	v_cvt_pk_bf16_f32 v97, v70, v71
	v_cvt_pk_bf16_f32 v98, v72, v73
	v_cvt_pk_bf16_f32 v99, v74, v75
	global_store_dwordx4 v13, v[96:99], s[64:65]
	s_waitcnt lgkmcnt(4)
	v_cvt_pk_bf16_f32 v100, v76, v77
	v_cvt_pk_bf16_f32 v101, v78, v79
	v_cvt_pk_bf16_f32 v102, v80, v81
	v_cvt_pk_bf16_f32 v103, v82, v83
	global_store_dwordx4 v14, v[100:103], s[64:65]
	s_waitcnt lgkmcnt(0)
	v_cvt_pk_bf16_f32 v104, v84, v85
	v_cvt_pk_bf16_f32 v105, v86, v87
	v_cvt_pk_bf16_f32 v106, v88, v89
	v_cvt_pk_bf16_f32 v107, v90, v91
	global_store_dwordx4 v15, v[104:107], s[64:65]
	s_cmpk_lt_i32 s32, 0x1600
	s_cbranch_scc0 .Lxpf0_fin
	s_add_i32 s59, s32, 0x400
	s_cmpk_lt_i32 s59, 0x1600
	s_cbranch_scc0 .Lxpf0_dumA
	s_lshr_b32 s64, s59, 6
	s_and_b32 s65, s59, 63
	s_mul_i32 s66, s64, 0x80000
	s_lshl_b32 s67, s65, 7
	s_add_i32 s66, s66, s67
	s_add_u32 s66, s60, s66
	s_addc_u32 s67, s61, 0
	v_mov_b32_e32 v11, v5
	global_load_dword v20, v11, s[66:67] nt
	v_add_u32_e32 v11, 0x4000, v11
	global_load_dword v21, v11, s[66:67] nt
	v_add_u32_e32 v11, 0x4000, v11
	global_load_dword v22, v11, s[66:67] nt
	v_add_u32_e32 v11, 0x4000, v11
	global_load_dword v23, v11, s[66:67] nt
	v_add_u32_e32 v11, 0x4000, v11
	global_load_dword v24, v11, s[66:67] nt
	v_add_u32_e32 v11, 0x4000, v11
	global_load_dword v25, v11, s[66:67] nt
	v_add_u32_e32 v11, 0x4000, v11
	global_load_dword v26, v11, s[66:67] nt
	v_add_u32_e32 v11, 0x4000, v11
	global_load_dword v27, v11, s[66:67] nt
	v_add_u32_e32 v11, 0x4000, v11
	global_load_dword v28, v11, s[66:67] nt
	v_add_u32_e32 v11, 0x4000, v11
	global_load_dword v29, v11, s[66:67] nt
	v_add_u32_e32 v11, 0x4000, v11
	global_load_dword v30, v11, s[66:67] nt
	v_add_u32_e32 v11, 0x4000, v11
	global_load_dword v31, v11, s[66:67] nt
	v_add_u32_e32 v11, 0x4000, v11
	global_load_dword v32, v11, s[66:67] nt
	v_add_u32_e32 v11, 0x4000, v11
	global_load_dword v33, v11, s[66:67] nt
	v_add_u32_e32 v11, 0x4000, v11
	global_load_dword v34, v11, s[66:67] nt
	v_add_u32_e32 v11, 0x4000, v11
	global_load_dword v35, v11, s[66:67] nt
	v_add_u32_e32 v11, 0x4000, v11
	global_load_dword v36, v11, s[66:67] nt
	v_add_u32_e32 v11, 0x4000, v11
	global_load_dword v37, v11, s[66:67] nt
	v_add_u32_e32 v11, 0x4000, v11
	global_load_dword v38, v11, s[66:67] nt
	v_add_u32_e32 v11, 0x4000, v11
	global_load_dword v39, v11, s[66:67] nt
	v_add_u32_e32 v11, 0x4000, v11
	global_load_dword v40, v11, s[66:67] nt
	v_add_u32_e32 v11, 0x4000, v11
	global_load_dword v41, v11, s[66:67] nt
	v_add_u32_e32 v11, 0x4000, v11
	global_load_dword v42, v11, s[66:67] nt
	v_add_u32_e32 v11, 0x4000, v11
	global_load_dword v43, v11, s[66:67] nt
	v_add_u32_e32 v11, 0x4000, v11
	global_load_dword v44, v11, s[66:67] nt
	v_add_u32_e32 v11, 0x4000, v11
	global_load_dword v45, v11, s[66:67] nt
	v_add_u32_e32 v11, 0x4000, v11
	global_load_dword v46, v11, s[66:67] nt
	v_add_u32_e32 v11, 0x4000, v11
	global_load_dword v47, v11, s[66:67] nt
	v_add_u32_e32 v11, 0x4000, v11
	global_load_dword v48, v11, s[66:67] nt
	v_add_u32_e32 v11, 0x4000, v11
	global_load_dword v49, v11, s[66:67] nt
	v_add_u32_e32 v11, 0x4000, v11
	global_load_dword v50, v11, s[66:67] nt
	v_add_u32_e32 v11, 0x4000, v11
	global_load_dword v51, v11, s[66:67] nt
	s_branch .Lxpf0_procB

; #define LAS __attribute__((address_space(3)))
; __device__ __forceinline__ unsigned cvt_pk_bf16(float lo, float hi) { unsigned r; asm volatile("v_cvt_pk_bf16_f32 %0, %1, %2" : "=v"(r) : "v"(lo), "v"(hi)); return r; }
; __device__ __forceinline__ void xpose_item(const float* src, int ld, bf16_t* dst, int K, int k0, LAS float* scr, int lane, const float* gk) {
;     if (src) {
; #pragma unroll 8
;         for (int i = 0; i < 32; ++i) { const int kk = 2 * i + (lane >> 5); scr[kk * 33 + (lane & 31)] = __builtin_nontemporal_load(src + (size_t)(k0 + kk) * ld + (lane & 31)); }
;     } else {
; #pragma unroll 8
;         for (int i = 0; i < 32; ++i) { const int kk = 2 * i + (lane >> 5); scr[kk * 33 + (lane & 31)] = 0.f; }
;     }
;     const int c = lane & 7;
;     f32x4 g0 = (f32x4){1.f, 1.f, 1.f, 1.f}, g1 = g0;
;     if (gk) { g0 = *(const f32x4*)(gk + k0 + 8 * c); g1 = *(const f32x4*)(gk + k0 + 8 * c + 4); }
;     asm volatile("s_waitcnt lgkmcnt(0)" ::: "memory");
; #pragma unroll
;     for (int j = 0; j < 4; ++j) { const int n = (lane >> 3) + 8 * j; const LAS float* s = scr + (8 * c) * 33 + n;
;         u32x4 o; o.x = cvt_pk_bf16(s[0 * 33] * g0[0], s[1 * 33] * g0[1]); o.y = cvt_pk_bf16(s[2 * 33] * g0[2], s[3 * 33] * g0[3]); o.z = cvt_pk_bf16(s[4 * 33] * g1[0], s[5 * 33] * g1[1]); o.w = cvt_pk_bf16(s[6 * 33] * g1[2], s[7 * 33] * g1[3]);
;         *(u32x4*)(dst + (size_t)n * K + k0 + 8 * c) = o; }
;     asm volatile("s_waitcnt lgkmcnt(0)" ::: "memory");
; }
; __global__ void __launch_bounds__(512) mega(Args a_byval) {
;     ...
;                 it = xpose_all(a.in[22], nullptr, 2048, 4096, 2048, 2048, 0, (bf16_t*)(ws + WS_WB_OUT), it, NGW, scr, lane);
.Lxpf0_end:
	s_sub_i32 s59, s59, 0x1600
	s_cmpk_ge_i32 s59, 0x1000
	s_cbranch_scc1 .Lxpwo_end
	s_load_dwordx2 s[60:61], s[92:93], 0xb0
	s_load_dwordx2 s[62:63], s[92:93], 0xe8
	v_mov_b32_e32 v5, 0x2000
	v_mul_u32_u24_e32 v5, v3, v5
	v_add_u32_e32 v5, v5, v4
	v_mov_b32_e32 v10, 0x2000
	v_mul_u32_u24_e32 v10, v8, v10
	v_lshl_add_u32 v12, v7, 4, v10
	v_add_u32_e32 v13, 0x10000, v12
	v_add_u32_e32 v14, 0x20000, v12
	v_add_u32_e32 v15, 0x30000, v12
	s_waitcnt lgkmcnt(0)
	s_add_u32 s62, s62, 0xad00000
	s_addc_u32 s63, s63, 0
	s_lshr_b32 s64, s59, 6
	s_and_b32 s65, s59, 63
	s_mul_i32 s66, s64, 0x80000
	s_lshl_b32 s67, s65, 7
	s_add_i32 s66, s66, s67
	s_add_u32 s66, s60, s66
	s_addc_u32 s67, s61, 0
	v_mov_b32_e32 v11, v5
	global_load_dword v20, v11, s[66:67] nt
	v_add_u32_e32 v11, 0x4000, v11
	global_load_dword v21, v11, s[66:67] nt
	v_add_u32_e32 v11, 0x4000, v11
	global_load_dword v22, v11, s[66:67] nt
	v_add_u32_e32 v11, 0x4000, v11
	global_load_dword v23, v11, s[66:67] nt
	v_add_u32_e32 v11, 0x4000, v11
	global_load_dword v24, v11, s[66:67] nt
	v_add_u32_e32 v11, 0x4000, v11
	global_load_dword v25, v11, s[66:67] nt
	v_add_u32_e32 v11, 0x4000, v11
	global_load_dword v26, v11, s[66:67] nt
	v_add_u32_e32 v11, 0x4000, v11
	global_load_dword v27, v11, s[66:67] nt
	v_add_u32_e32 v11, 0x4000, v11
	global_load_dword v28, v11, s[66:67] nt
	v_add_u32_e32 v11, 0x4000, v11
	global_load_dword v29, v11, s[66:67] nt
	v_add_u32_e32 v11, 0x4000, v11
	global_load_dword v30, v11, s[66:67] nt
	v_add_u32_e32 v11, 0x4000, v11
	global_load_dword v31, v11, s[66:67] nt
	v_add_u32_e32 v11, 0x4000, v11
	global_load_dword v32, v11, s[66:67] nt
	v_add_u32_e32 v11, 0x4000, v11
	global_load_dword v33, v11, s[66:67] nt
	v_add_u32_e32 v11, 0x4000, v11
	global_load_dword v34, v11, s[66:67] nt
	v_add_u32_e32 v11, 0x4000, v11
	global_load_dword v35, v11, s[66:67] nt
	v_add_u32_e32 v11, 0x4000, v11
	global_load_dword v36, v11, s[66:67] nt
	v_add_u32_e32 v11, 0x4000, v11
	global_load_dword v37, v11, s[66:67] nt
	v_add_u32_e32 v11, 0x4000, v11
	global_load_dword v38, v11, s[66:67] nt
	v_add_u32_e32 v11, 0x4000, v11
	global_load_dword v39, v11, s[66:67] nt
	v_add_u32_e32 v11, 0x4000, v11
	global_load_dword v40, v11, s[66:67] nt
	v_add_u32_e32 v11, 0x4000, v11
	global_load_dword v41, v11, s[66:67] nt
	v_add_u32_e32 v11, 0x4000, v11
	global_load_dword v42, v11, s[66:67] nt
	v_add_u32_e32 v11, 0x4000, v11
	global_load_dword v43, v11, s[66:67] nt
	v_add_u32_e32 v11, 0x4000, v11
	global_load_dword v44, v11, s[66:67] nt
	v_add_u32_e32 v11, 0x4000, v11
	global_load_dword v45, v11, s[66:67] nt
	v_add_u32_e32 v11, 0x4000, v11
	global_load_dword v46, v11, s[66:67] nt
	v_add_u32_e32 v11, 0x4000, v11
	global_load_dword v47, v11, s[66:67] nt
	v_add_u32_e32 v11, 0x4000, v11
	global_load_dword v48, v11, s[66:67] nt
	v_add_u32_e32 v11, 0x4000, v11
	global_load_dword v49, v11, s[66:67] nt
	v_add_u32_e32 v11, 0x4000, v11
	global_load_dword v50, v11, s[66:67] nt
	v_add_u32_e32 v11, 0x4000, v11
	global_load_dword v51, v11, s[66:67] nt
.Lxpwo_loop:
	s_add_i32 s32, s59, 0x400
	s_cmpk_lt_i32 s32, 0x1000
	s_cbranch_scc0 .Lxpwo_dumB
	s_lshr_b32 s64, s32, 6
	s_and_b32 s65, s32, 63
	s_mul_i32 s66, s64, 0x80000
	s_lshl_b32 s67, s65, 7
	s_add_i32 s66, s66, s67
	s_add_u32 s66, s60, s66
	s_addc_u32 s67, s61, 0
	v_mov_b32_e32 v11, v5
	global_load_dword v108, v11, s[66:67] nt
	v_add_u32_e32 v11, 0x4000, v11
	global_load_dword v109, v11, s[66:67] nt
	v_add_u32_e32 v11, 0x4000, v11
	global_load_dword v110, v11, s[66:67] nt
	v_add_u32_e32 v11, 0x4000, v11
	global_load_dword v111, v11, s[66:67] nt
	v_add_u32_e32 v11, 0x4000, v11
	global_load_dword v112, v11, s[66:67] nt
	v_add_u32_e32 v11, 0x4000, v11
	global_load_dword v113, v11, s[66:67] nt
	v_add_u32_e32 v11, 0x4000, v11
	global_load_dword v114, v11, s[66:67] nt
	v_add_u32_e32 v11, 0x4000, v11
	global_load_dword v115, v11, s[66:67] nt
	v_add_u32_e32 v11, 0x4000, v11
	global_load_dword v116, v11, s[66:67] nt
	v_add_u32_e32 v11, 0x4000, v11
	global_load_dword v117, v11, s[66:67] nt
	v_add_u32_e32 v11, 0x4000, v11
	global_load_dword v118, v11, s[66:67] nt
	v_add_u32_e32 v11, 0x4000, v11
	global_load_dword v119, v11, s[66:67] nt
	v_add_u32_e32 v11, 0x4000, v11
	global_load_dword v120, v11, s[66:67] nt
	v_add_u32_e32 v11, 0x4000, v11
	global_load_dword v121, v11, s[66:67] nt
	v_add_u32_e32 v11, 0x4000, v11
	global_load_dword v122, v11, s[66:67] nt
	v_add_u32_e32 v11, 0x4000, v11
	global_load_dword v123, v11, s[66:67] nt
	v_add_u32_e32 v11, 0x4000, v11
	global_load_dword v124, v11, s[66:67] nt
	v_add_u32_e32 v11, 0x4000, v11
	global_load_dword v125, v11, s[66:67] nt
	v_add_u32_e32 v11, 0x4000, v11
	global_load_dword v126, v11, s[66:67] nt
	v_add_u32_e32 v11, 0x4000, v11
	global_load_dword v127, v11, s[66:67] nt
	v_add_u32_e32 v11, 0x4000, v11
	global_load_dword v128, v11, s[66:67] nt
	v_add_u32_e32 v11, 0x4000, v11
	global_load_dword v129, v11, s[66:67] nt
	v_add_u32_e32 v11, 0x4000, v11
	global_load_dword v130, v11, s[66:67] nt
	v_add_u32_e32 v11, 0x4000, v11
	global_load_dword v131, v11, s[66:67] nt
	v_add_u32_e32 v11, 0x4000, v11
	global_load_dword v132, v11, s[66:67] nt
	v_add_u32_e32 v11, 0x4000, v11
	global_load_dword v133, v11, s[66:67] nt
	v_add_u32_e32 v11, 0x4000, v11
	global_load_dword v134, v11, s[66:67] nt
	v_add_u32_e32 v11, 0x4000, v11
	global_load_dword v135, v11, s[66:67] nt
	v_add_u32_e32 v11, 0x4000, v11
	global_load_dword v136, v11, s[66:67] nt
	v_add_u32_e32 v11, 0x4000, v11
	global_load_dword v137, v11, s[66:67] nt
	v_add_u32_e32 v11, 0x4000, v11
	global_load_dword v138, v11, s[66:67] nt
	v_add_u32_e32 v11, 0x4000, v11
	global_load_dword v139, v11, s[66:67] nt
	s_branch .Lxpwo_procA

; #define LAS __attribute__((address_space(3)))
; __device__ __forceinline__ unsigned cvt_pk_bf16(float lo, float hi) { unsigned r; asm volatile("v_cvt_pk_bf16_f32 %0, %1, %2" : "=v"(r) : "v"(lo), "v"(hi)); return r; }
; __device__ __forceinline__ void xpose_item(const float* src, int ld, bf16_t* dst, int K, int k0, LAS float* scr, int lane, const float* gk) {
;     if (src) {
; #pragma unroll 8
;         for (int i = 0; i < 32; ++i) { const int kk = 2 * i + (lane >> 5); scr[kk * 33 + (lane & 31)] = __builtin_nontemporal_load(src + (size_t)(k0 + kk) * ld + (lane & 31)); }
;     } else {
; #pragma unroll 8
;         for (int i = 0; i < 32; ++i) { const int kk = 2 * i + (lane >> 5); scr[kk * 33 + (lane & 31)] = 0.f; }
;     }
;     const int c = lane & 7;
;     f32x4 g0 = (f32x4){1.f, 1.f, 1.f, 1.f}, g1 = g0;
;     if (gk) { g0 = *(const f32x4*)(gk + k0 + 8 * c); g1 = *(const f32x4*)(gk + k0 + 8 * c + 4); }
;     asm volatile("s_waitcnt lgkmcnt(0)" ::: "memory");
; #pragma unroll
;     for (int j = 0; j < 4; ++j) { const int n = (lane >> 3) + 8 * j; const LAS float* s = scr + (8 * c) * 33 + n;
;         u32x4 o; o.x = cvt_pk_bf16(s[0 * 33] * g0[0], s[1 * 33] * g0[1]); o.y = cvt_pk_bf16(s[2 * 33] * g0[2], s[3 * 33] * g0[3]); o.z = cvt_pk_bf16(s[4 * 33] * g1[0], s[5 * 33] * g1[1]); o.w = cvt_pk_bf16(s[6 * 33] * g1[2], s[7 * 33] * g1[3]);
;         *(u32x4*)(dst + (size_t)n * K + k0 + 8 * c) = o; }
;     asm volatile("s_waitcnt lgkmcnt(0)" ::: "memory");
; }
; __global__ void __launch_bounds__(512) mega(Args a_byval) {
;     ...
;                 it = xpose_all(a.in[22], nullptr, 2048, 4096, 2048, 2048, 0, (bf16_t*)(ws + WS_WB_OUT), it, NGW, scr, lane);
.Lxpwo_procA:
	s_lshr_b32 s64, s59, 6
	s_and_b32 s65, s59, 63
	s_mul_i32 s68, s65, 0x40000
	s_lshl_b32 s64, s64, 7
	s_add_i32 s68, s68, s64
	s_add_u32 s64, s62, s68
	s_addc_u32 s65, s63, 0
	s_waitcnt vmcnt(63)
	ds_write_b32 v6, v20 offset:0
	s_waitcnt vmcnt(62)
	ds_write_b32 v6, v21 offset:264
	s_waitcnt vmcnt(61)
	ds_write_b32 v6, v22 offset:528
	s_waitcnt vmcnt(60)
	ds_write_b32 v6, v23 offset:792
	s_waitcnt vmcnt(59)
	ds_write_b32 v6, v24 offset:1056
	s_waitcnt vmcnt(58)
	ds_write_b32 v6, v25 offset:1320
	s_waitcnt vmcnt(57)
	ds_write_b32 v6, v26 offset:1584
	s_waitcnt vmcnt(56)
	ds_write_b32 v6, v27 offset:1848
	s_waitcnt vmcnt(55)
	ds_write_b32 v6, v28 offset:2112
	s_waitcnt vmcnt(54)
	ds_write_b32 v6, v29 offset:2376
	s_waitcnt vmcnt(53)
	ds_write_b32 v6, v30 offset:2640
	s_waitcnt vmcnt(52)
	ds_write_b32 v6, v31 offset:2904
	s_waitcnt vmcnt(51)
	ds_write_b32 v6, v32 offset:3168
	s_waitcnt vmcnt(50)
	ds_write_b32 v6, v33 offset:3432
	s_waitcnt vmcnt(49)
	ds_write_b32 v6, v34 offset:3696
	s_waitcnt vmcnt(48)
	ds_write_b32 v6, v35 offset:3960
	s_waitcnt vmcnt(47)
	ds_write_b32 v6, v36 offset:4224
	s_waitcnt vmcnt(46)
	ds_write_b32 v6, v37 offset:4488
	s_waitcnt vmcnt(45)
	ds_write_b32 v6, v38 offset:4752
	s_waitcnt vmcnt(44)
	ds_write_b32 v6, v39 offset:5016
	s_waitcnt vmcnt(43)
	ds_write_b32 v6, v40 offset:5280
	s_waitcnt vmcnt(42)
	ds_write_b32 v6, v41 offset:5544
	s_waitcnt vmcnt(41)
	ds_write_b32 v6, v42 offset:5808
	s_waitcnt vmcnt(40)
	ds_write_b32 v6, v43 offset:6072
	s_waitcnt vmcnt(39)
	ds_write_b32 v6, v44 offset:6336
	s_waitcnt vmcnt(38)
	ds_write_b32 v6, v45 offset:6600
	s_waitcnt vmcnt(37)
	ds_write_b32 v6, v46 offset:6864
	s_waitcnt vmcnt(36)
	ds_write_b32 v6, v47 offset:7128
	s_waitcnt vmcnt(35)
	ds_write_b32 v6, v48 offset:7392
	s_waitcnt vmcnt(34)
	ds_write_b32 v6, v49 offset:7656
	s_waitcnt vmcnt(33)
	ds_write_b32 v6, v50 offset:7920
	s_waitcnt vmcnt(32)
	ds_write_b32 v6, v51 offset:8184
	s_waitcnt lgkmcnt(0)
	ds_read2_b32 v[60:61], v9 offset0:0 offset1:33
	ds_read2_b32 v[62:63], v9 offset0:66 offset1:99
	ds_read2_b32 v[64:65], v9 offset0:132 offset1:165
	ds_read2_b32 v[66:67], v9 offset0:198 offset1:231
	ds_read2_b32 v[68:69], v9 offset0:8 offset1:41
	ds_read2_b32 v[70:71], v9 offset0:74 offset1:107
	ds_read2_b32 v[72:73], v9 offset0:140 offset1:173
	ds_read2_b32 v[74:75], v9 offset0:206 offset1:239
	ds_read2_b32 v[76:77], v9 offset0:16 offset1:49
	ds_read2_b32 v[78:79], v9 offset0:82 offset1:115
	ds_read2_b32 v[80:81], v9 offset0:148 offset1:181
	ds_read2_b32 v[82:83], v9 offset0:214 offset1:247
	ds_read2_b32 v[84:85], v9 offset0:24 offset1:57
	ds_read2_b32 v[86:87], v9 offset0:90 offset1:123
	ds_read2_b32 v[88:89], v9 offset0:156 offset1:189
	ds_read2_b32 v[90:91], v9 offset0:222 offset1:255
	s_waitcnt lgkmcnt(12)
	v_cvt_pk_bf16_f32 v92, v60, v61
	v_cvt_pk_bf16_f32 v93, v62, v63
	v_cvt_pk_bf16_f32 v94, v64, v65
	v_cvt_pk_bf16_f32 v95, v66, v67
	global_store_dwordx4 v12, v[92:95], s[64:65]
	s_waitcnt lgkmcnt(8)
	v_cvt_pk_bf16_f32 v96, v68, v69
	v_cvt_pk_bf16_f32 v97, v70, v71
	v_cvt_pk_bf16_f32 v98, v72, v73
	v_cvt_pk_bf16_f32 v99, v74, v75
	global_store_dwordx4 v13, v[96:99], s[64:65]
	s_waitcnt lgkmcnt(4)
	v_cvt_pk_bf16_f32 v100, v76, v77
	v_cvt_pk_bf16_f32 v101, v78, v79
	v_cvt_pk_bf16_f32 v102, v80, v81
	v_cvt_pk_bf16_f32 v103, v82, v83
	global_store_dwordx4 v14, v[100:103], s[64:65]
	s_waitcnt lgkmcnt(0)
	v_cvt_pk_bf16_f32 v104, v84, v85
	v_cvt_pk_bf16_f32 v105, v86, v87
	v_cvt_pk_bf16_f32 v106, v88, v89
	v_cvt_pk_bf16_f32 v107, v90, v91
	global_store_dwordx4 v15, v[104:107], s[64:65]
	s_cmpk_lt_i32 s32, 0x1000
	s_cbranch_scc0 .Lxpwo_fin
	s_add_i32 s59, s32, 0x400
	s_cmpk_lt_i32 s59, 0x1000
	s_cbranch_scc0 .Lxpwo_dumA
	s_lshr_b32 s64, s59, 6
	s_and_b32 s65, s59, 63
	s_mul_i32 s66, s64, 0x80000
	s_lshl_b32 s67, s65, 7
	s_add_i32 s66, s66, s67
	s_add_u32 s66, s60, s66
	s_addc_u32 s67, s61, 0
	v_mov_b32_e32 v11, v5
	global_load_dword v20, v11, s[66:67] nt
	v_add_u32_e32 v11, 0x4000, v11
	global_load_dword v21, v11, s[66:67] nt
	v_add_u32_e32 v11, 0x4000, v11
	global_load_dword v22, v11, s[66:67] nt
	v_add_u32_e32 v11, 0x4000, v11
	global_load_dword v23, v11, s[66:67] nt
	v_add_u32_e32 v11, 0x4000, v11
	global_load_dword v24, v11, s[66:67] nt
	v_add_u32_e32 v11, 0x4000, v11
	global_load_dword v25, v11, s[66:67] nt
	v_add_u32_e32 v11, 0x4000, v11
	global_load_dword v26, v11, s[66:67] nt
	v_add_u32_e32 v11, 0x4000, v11
	global_load_dword v27, v11, s[66:67] nt
	v_add_u32_e32 v11, 0x4000, v11
	global_load_dword v28, v11, s[66:67] nt
	v_add_u32_e32 v11, 0x4000, v11
	global_load_dword v29, v11, s[66:67] nt
	v_add_u32_e32 v11, 0x4000, v11
	global_load_dword v30, v11, s[66:67] nt
	v_add_u32_e32 v11, 0x4000, v11
	global_load_dword v31, v11, s[66:67] nt
	v_add_u32_e32 v11, 0x4000, v11
	global_load_dword v32, v11, s[66:67] nt
	v_add_u32_e32 v11, 0x4000, v11
	global_load_dword v33, v11, s[66:67] nt
	v_add_u32_e32 v11, 0x4000, v11
	global_load_dword v34, v11, s[66:67] nt
	v_add_u32_e32 v11, 0x4000, v11
	global_load_dword v35, v11, s[66:67] nt
	v_add_u32_e32 v11, 0x4000, v11
	global_load_dword v36, v11, s[66:67] nt
	v_add_u32_e32 v11, 0x4000, v11
	global_load_dword v37, v11, s[66:67] nt
	v_add_u32_e32 v11, 0x4000, v11
	global_load_dword v38, v11, s[66:67] nt
	v_add_u32_e32 v11, 0x4000, v11
	global_load_dword v39, v11, s[66:67] nt
	v_add_u32_e32 v11, 0x4000, v11
	global_load_dword v40, v11, s[66:67] nt
	v_add_u32_e32 v11, 0x4000, v11
	global_load_dword v41, v11, s[66:67] nt
	v_add_u32_e32 v11, 0x4000, v11
	global_load_dword v42, v11, s[66:67] nt
	v_add_u32_e32 v11, 0x4000, v11
	global_load_dword v43, v11, s[66:67] nt
	v_add_u32_e32 v11, 0x4000, v11
	global_load_dword v44, v11, s[66:67] nt
	v_add_u32_e32 v11, 0x4000, v11
	global_load_dword v45, v11, s[66:67] nt
	v_add_u32_e32 v11, 0x4000, v11
	global_load_dword v46, v11, s[66:67] nt
	v_add_u32_e32 v11, 0x4000, v11
	global_load_dword v47, v11, s[66:67] nt
	v_add_u32_e32 v11, 0x4000, v11
	global_load_dword v48, v11, s[66:67] nt
	v_add_u32_e32 v11, 0x4000, v11
	global_load_dword v49, v11, s[66:67] nt
	v_add_u32_e32 v11, 0x4000, v11
	global_load_dword v50, v11, s[66:67] nt
	v_add_u32_e32 v11, 0x4000, v11
	global_load_dword v51, v11, s[66:67] nt
	s_branch .Lxpwo_procB

; #define LAS __attribute__((address_space(3)))
; __device__ __forceinline__ unsigned cvt_pk_bf16(float lo, float hi) { unsigned r; asm volatile("v_cvt_pk_bf16_f32 %0, %1, %2" : "=v"(r) : "v"(lo), "v"(hi)); return r; }
; __device__ __forceinline__ void xpose_item(const float* src, int ld, bf16_t* dst, int K, int k0, LAS float* scr, int lane, const float* gk) {
;     if (src) {
; #pragma unroll 8
;         for (int i = 0; i < 32; ++i) { const int kk = 2 * i + (lane >> 5); scr[kk * 33 + (lane & 31)] = __builtin_nontemporal_load(src + (size_t)(k0 + kk) * ld + (lane & 31)); }
;     } else {
; #pragma unroll 8
;         for (int i = 0; i < 32; ++i) { const int kk = 2 * i + (lane >> 5); scr[kk * 33 + (lane & 31)] = 0.f; }
;     }
;     const int c = lane & 7;
;     f32x4 g0 = (f32x4){1.f, 1.f, 1.f, 1.f}, g1 = g0;
;     if (gk) { g0 = *(const f32x4*)(gk + k0 + 8 * c); g1 = *(const f32x4*)(gk + k0 + 8 * c + 4); }
;     asm volatile("s_waitcnt lgkmcnt(0)" ::: "memory");
; #pragma unroll
;     for (int j = 0; j < 4; ++j) { const int n = (lane >> 3) + 8 * j; const LAS float* s = scr + (8 * c) * 33 + n;
;         u32x4 o; o.x = cvt_pk_bf16(s[0 * 33] * g0[0], s[1 * 33] * g0[1]); o.y = cvt_pk_bf16(s[2 * 33] * g0[2], s[3 * 33] * g0[3]); o.z = cvt_pk_bf16(s[4 * 33] * g1[0], s[5 * 33] * g1[1]); o.w = cvt_pk_bf16(s[6 * 33] * g1[2], s[7 * 33] * g1[3]);
;         *(u32x4*)(dst + (size_t)n * K + k0 + 8 * c) = o; }
;     asm volatile("s_waitcnt lgkmcnt(0)" ::: "memory");
; }
; __global__ void __launch_bounds__(512) mega(Args a_byval) {
;     ...
;                 it = xpose_all(a.in[15], nullptr, SSD_IN, 2048, SSD_IN, SSD_IN, 0, (bf16_t*)(ws + WS_WB_IN), it, NGW, scr, lane, norm_mix_g + D);
.Lxpwo_end:
	s_sub_i32 s59, s59, 0x1000
	s_cmpk_ge_i32 s59, 0x2840
	s_cbranch_scc1 .Lxpwi_end
	s_load_dwordx2 s[60:61], s[92:93], 0x78
	s_load_dwordx2 s[62:63], s[92:93], 0xe8
	s_load_dwordx2 s[64:65], s[92:93], 0x10
	v_mov_b32_e32 v5, 0xa100
	v_mul_u32_u24_e32 v5, v3, v5
	v_add_u32_e32 v5, v5, v4
	v_mov_b32_e32 v10, 0x1000
	v_mul_u32_u24_e32 v10, v8, v10
	v_lshl_add_u32 v12, v7, 4, v10
	v_add_u32_e32 v13, 0x8000, v12
	v_add_u32_e32 v14, 0x10000, v12
	v_add_u32_e32 v15, 0x18000, v12
	s_waitcnt lgkmcnt(0)
	s_add_u32 s62, s62, 0x8400000
	s_addc_u32 s63, s63, 0
	s_add_u32 s64, s64, 0x2000
	s_addc_u32 s65, s65, 0
	v_lshlrev_b32_e32 v16, 5, v7
	v_mov_b32_e32 v17, v0
	v_lshl_add_u64 v[16:17], s[64:65], 0, v[16:17]
	s_mul_hi_u32 s64, s59, 0xcb8728
	s_mul_i32 s65, s64, 0x142
	s_sub_i32 s65, s59, s65
	s_mul_i32 s66, s64, 0x284000
	s_lshl_b32 s67, s65, 7
	s_add_i32 s66, s66, s67
	s_add_u32 s66, s60, s66
	s_addc_u32 s67, s61, 0
	s_lshl_b32 s64, s64, 8
	s_mov_b32 s65, 0
	v_lshl_add_u64 v[18:19], s[64:65], 0, v[16:17]
	global_load_dwordx4 v[52:55], v[18:19], off
	global_load_dwordx4 v[56:59], v[18:19], off offset:16
	v_mov_b32_e32 v11, v5
	global_load_dword v20, v11, s[66:67] nt
	v_add_u32_e32 v11, 0x14200, v11
	global_load_dword v21, v11, s[66:67] nt
	v_add_u32_e32 v11, 0x14200, v11
	global_load_dword v22, v11, s[66:67] nt
	v_add_u32_e32 v11, 0x14200, v11
	global_load_dword v23, v11, s[66:67] nt
	v_add_u32_e32 v11, 0x14200, v11
	global_load_dword v24, v11, s[66:67] nt
	v_add_u32_e32 v11, 0x14200, v11
	global_load_dword v25, v11, s[66:67] nt
	v_add_u32_e32 v11, 0x14200, v11
	global_load_dword v26, v11, s[66:67] nt
	v_add_u32_e32 v11, 0x14200, v11
	global_load_dword v27, v11, s[66:67] nt
	v_add_u32_e32 v11, 0x14200, v11
	global_load_dword v28, v11, s[66:67] nt
	v_add_u32_e32 v11, 0x14200, v11
	global_load_dword v29, v11, s[66:67] nt
	v_add_u32_e32 v11, 0x14200, v11
	global_load_dword v30, v11, s[66:67] nt
	v_add_u32_e32 v11, 0x14200, v11
	global_load_dword v31, v11, s[66:67] nt
	v_add_u32_e32 v11, 0x14200, v11
	global_load_dword v32, v11, s[66:67] nt
	v_add_u32_e32 v11, 0x14200, v11
	global_load_dword v33, v11, s[66:67] nt
	v_add_u32_e32 v11, 0x14200, v11
	global_load_dword v34, v11, s[66:67] nt
	v_add_u32_e32 v11, 0x14200, v11
	global_load_dword v35, v11, s[66:67] nt
	v_add_u32_e32 v11, 0x14200, v11
	global_load_dword v36, v11, s[66:67] nt
	v_add_u32_e32 v11, 0x14200, v11
	global_load_dword v37, v11, s[66:67] nt
	v_add_u32_e32 v11, 0x14200, v11
	global_load_dword v38, v11, s[66:67] nt
	v_add_u32_e32 v11, 0x14200, v11
	global_load_dword v39, v11, s[66:67] nt
	v_add_u32_e32 v11, 0x14200, v11
	global_load_dword v40, v11, s[66:67] nt
	v_add_u32_e32 v11, 0x14200, v11
	global_load_dword v41, v11, s[66:67] nt
	v_add_u32_e32 v11, 0x14200, v11
	global_load_dword v42, v11, s[66:67] nt
	v_add_u32_e32 v11, 0x14200, v11
	global_load_dword v43, v11, s[66:67] nt
	v_add_u32_e32 v11, 0x14200, v11
	global_load_dword v44, v11, s[66:67] nt
	v_add_u32_e32 v11, 0x14200, v11
	global_load_dword v45, v11, s[66:67] nt
	v_add_u32_e32 v11, 0x14200, v11
	global_load_dword v46, v11, s[66:67] nt
	v_add_u32_e32 v11, 0x14200, v11
	global_load_dword v47, v11, s[66:67] nt
	v_add_u32_e32 v11, 0x14200, v11
	global_load_dword v48, v11, s[66:67] nt
	v_add_u32_e32 v11, 0x14200, v11
	global_load_dword v49, v11, s[66:67] nt
	v_add_u32_e32 v11, 0x14200, v11
	global_load_dword v50, v11, s[66:67] nt
	v_add_u32_e32 v11, 0x14200, v11
	global_load_dword v51, v11, s[66:67] nt
.Lxpwi_loop:
	s_add_i32 s32, s59, 0x400
	s_cmpk_lt_i32 s32, 0x2840
	s_cbranch_scc0 .Lxpwi_dumB
	s_mul_hi_u32 s64, s32, 0xcb8728
	s_mul_i32 s65, s64, 0x142
	s_sub_i32 s65, s32, s65
	s_mul_i32 s66, s64, 0x284000
	s_lshl_b32 s67, s65, 7
	s_add_i32 s66, s66, s67
	s_add_u32 s66, s60, s66
	s_addc_u32 s67, s61, 0
	s_lshl_b32 s64, s64, 8
	s_mov_b32 s65, 0
	v_lshl_add_u64 v[18:19], s[64:65], 0, v[16:17]
	global_load_dwordx4 v[160:163], v[18:19], off
	global_load_dwordx4 v[164:167], v[18:19], off offset:16
	v_mov_b32_e32 v11, v5
	global_load_dword v108, v11, s[66:67] nt
	v_add_u32_e32 v11, 0x14200, v11
	global_load_dword v109, v11, s[66:67] nt
	v_add_u32_e32 v11, 0x14200, v11
	global_load_dword v110, v11, s[66:67] nt
	v_add_u32_e32 v11, 0x14200, v11
	global_load_dword v111, v11, s[66:67] nt
	v_add_u32_e32 v11, 0x14200, v11
	global_load_dword v112, v11, s[66:67] nt
	v_add_u32_e32 v11, 0x14200, v11
	global_load_dword v113, v11, s[66:67] nt
	v_add_u32_e32 v11, 0x14200, v11
	global_load_dword v114, v11, s[66:67] nt
	v_add_u32_e32 v11, 0x14200, v11
	global_load_dword v115, v11, s[66:67] nt
	v_add_u32_e32 v11, 0x14200, v11
	global_load_dword v116, v11, s[66:67] nt
	v_add_u32_e32 v11, 0x14200, v11
	global_load_dword v117, v11, s[66:67] nt
	v_add_u32_e32 v11, 0x14200, v11
	global_load_dword v118, v11, s[66:67] nt
	v_add_u32_e32 v11, 0x14200, v11
	global_load_dword v119, v11, s[66:67] nt
	v_add_u32_e32 v11, 0x14200, v11
	global_load_dword v120, v11, s[66:67] nt
	v_add_u32_e32 v11, 0x14200, v11
	global_load_dword v121, v11, s[66:67] nt
	v_add_u32_e32 v11, 0x14200, v11
	global_load_dword v122, v11, s[66:67] nt
	v_add_u32_e32 v11, 0x14200, v11
	global_load_dword v123, v11, s[66:67] nt
	v_add_u32_e32 v11, 0x14200, v11
	global_load_dword v124, v11, s[66:67] nt
	v_add_u32_e32 v11, 0x14200, v11
	global_load_dword v125, v11, s[66:67] nt
	v_add_u32_e32 v11, 0x14200, v11
	global_load_dword v126, v11, s[66:67] nt
	v_add_u32_e32 v11, 0x14200, v11
	global_load_dword v127, v11, s[66:67] nt
	v_add_u32_e32 v11, 0x14200, v11
	global_load_dword v128, v11, s[66:67] nt
	v_add_u32_e32 v11, 0x14200, v11
	global_load_dword v129, v11, s[66:67] nt
	v_add_u32_e32 v11, 0x14200, v11
	global_load_dword v130, v11, s[66:67] nt
	v_add_u32_e32 v11, 0x14200, v11
	global_load_dword v131, v11, s[66:67] nt
	v_add_u32_e32 v11, 0x14200, v11
	global_load_dword v132, v11, s[66:67] nt
	v_add_u32_e32 v11, 0x14200, v11
	global_load_dword v133, v11, s[66:67] nt
	v_add_u32_e32 v11, 0x14200, v11
	global_load_dword v134, v11, s[66:67] nt
	v_add_u32_e32 v11, 0x14200, v11
	global_load_dword v135, v11, s[66:67] nt
	v_add_u32_e32 v11, 0x14200, v11
	global_load_dword v136, v11, s[66:67] nt
	v_add_u32_e32 v11, 0x14200, v11
	global_load_dword v137, v11, s[66:67] nt
	v_add_u32_e32 v11, 0x14200, v11
	global_load_dword v138, v11, s[66:67] nt
	v_add_u32_e32 v11, 0x14200, v11
	global_load_dword v139, v11, s[66:67] nt
	s_branch .Lxpwi_procA

; #define LAS __attribute__((address_space(3)))
; __device__ __forceinline__ unsigned cvt_pk_bf16(float lo, float hi) { unsigned r; asm volatile("v_cvt_pk_bf16_f32 %0, %1, %2" : "=v"(r) : "v"(lo), "v"(hi)); return r; }
; __device__ __forceinline__ void xpose_item(const float* src, int ld, bf16_t* dst, int K, int k0, LAS float* scr, int lane, const float* gk) {
;     if (src) {
; #pragma unroll 8
;         for (int i = 0; i < 32; ++i) { const int kk = 2 * i + (lane >> 5); scr[kk * 33 + (lane & 31)] = __builtin_nontemporal_load(src + (size_t)(k0 + kk) * ld + (lane & 31)); }
;     } else {
; #pragma unroll 8
;         for (int i = 0; i < 32; ++i) { const int kk = 2 * i + (lane >> 5); scr[kk * 33 + (lane & 31)] = 0.f; }
;     }
;     const int c = lane & 7;
;     f32x4 g0 = (f32x4){1.f, 1.f, 1.f, 1.f}, g1 = g0;
;     if (gk) { g0 = *(const f32x4*)(gk + k0 + 8 * c); g1 = *(const f32x4*)(gk + k0 + 8 * c + 4); }
;     asm volatile("s_waitcnt lgkmcnt(0)" ::: "memory");
; #pragma unroll
;     for (int j = 0; j < 4; ++j) { const int n = (lane >> 3) + 8 * j; const LAS float* s = scr + (8 * c) * 33 + n;
;         u32x4 o; o.x = cvt_pk_bf16(s[0 * 33] * g0[0], s[1 * 33] * g0[1]); o.y = cvt_pk_bf16(s[2 * 33] * g0[2], s[3 * 33] * g0[3]); o.z = cvt_pk_bf16(s[4 * 33] * g1[0], s[5 * 33] * g1[1]); o.w = cvt_pk_bf16(s[6 * 33] * g1[2], s[7 * 33] * g1[3]);
;         *(u32x4*)(dst + (size_t)n * K + k0 + 8 * c) = o; }
;     asm volatile("s_waitcnt lgkmcnt(0)" ::: "memory");
; }
; __global__ void __launch_bounds__(512) mega(Args a_byval) {
;     ...
;                 it = xpose_all(a.in[15], nullptr, SSD_IN, 2048, SSD_IN, SSD_IN, 0, (bf16_t*)(ws + WS_WB_IN), it, NGW, scr, lane, norm_mix_g + D);
.Lxpwi_procA:
	s_mul_hi_u32 s64, s59, 0xcb8728
	s_mul_i32 s65, s64, 0x142
	s_sub_i32 s65, s59, s65
	s_mul_i32 s68, s65, 0x20000
	s_lshl_b32 s64, s64, 7
	s_add_i32 s68, s68, s64
	s_add_u32 s64, s62, s68
	s_addc_u32 s65, s63, 0
	s_waitcnt vmcnt(63)
	ds_write_b32 v6, v20 offset:0
	s_waitcnt vmcnt(62)
	ds_write_b32 v6, v21 offset:264
	s_waitcnt vmcnt(61)
	ds_write_b32 v6, v22 offset:528
	s_waitcnt vmcnt(60)
	ds_write_b32 v6, v23 offset:792
	s_waitcnt vmcnt(59)
	ds_write_b32 v6, v24 offset:1056
	s_waitcnt vmcnt(58)
	ds_write_b32 v6, v25 offset:1320
	s_waitcnt vmcnt(57)
	ds_write_b32 v6, v26 offset:1584
	s_waitcnt vmcnt(56)
	ds_write_b32 v6, v27 offset:1848
	s_waitcnt vmcnt(55)
	ds_write_b32 v6, v28 offset:2112
	s_waitcnt vmcnt(54)
	ds_write_b32 v6, v29 offset:2376
	s_waitcnt vmcnt(53)
	ds_write_b32 v6, v30 offset:2640
	s_waitcnt vmcnt(52)
	ds_write_b32 v6, v31 offset:2904
	s_waitcnt vmcnt(51)
	ds_write_b32 v6, v32 offset:3168
	s_waitcnt vmcnt(50)
	ds_write_b32 v6, v33 offset:3432
	s_waitcnt vmcnt(49)
	ds_write_b32 v6, v34 offset:3696
	s_waitcnt vmcnt(48)
	ds_write_b32 v6, v35 offset:3960
	s_waitcnt vmcnt(47)
	ds_write_b32 v6, v36 offset:4224
	s_waitcnt vmcnt(46)
	ds_write_b32 v6, v37 offset:4488
	s_waitcnt vmcnt(45)
	ds_write_b32 v6, v38 offset:4752
	s_waitcnt vmcnt(44)
	ds_write_b32 v6, v39 offset:5016
	s_waitcnt vmcnt(43)
	ds_write_b32 v6, v40 offset:5280
	s_waitcnt vmcnt(42)
	ds_write_b32 v6, v41 offset:5544
	s_waitcnt vmcnt(41)
	ds_write_b32 v6, v42 offset:5808
	s_waitcnt vmcnt(40)
	ds_write_b32 v6, v43 offset:6072
	s_waitcnt vmcnt(39)
	ds_write_b32 v6, v44 offset:6336
	s_waitcnt vmcnt(38)
	ds_write_b32 v6, v45 offset:6600
	s_waitcnt vmcnt(37)
	ds_write_b32 v6, v46 offset:6864
	s_waitcnt vmcnt(36)
	ds_write_b32 v6, v47 offset:7128
	s_waitcnt vmcnt(35)
	ds_write_b32 v6, v48 offset:7392
	s_waitcnt vmcnt(34)
	ds_write_b32 v6, v49 offset:7656
	s_waitcnt vmcnt(33)
	ds_write_b32 v6, v50 offset:7920
	s_waitcnt vmcnt(32)
	ds_write_b32 v6, v51 offset:8184
	s_waitcnt lgkmcnt(0)
	ds_read2_b32 v[60:61], v9 offset0:0 offset1:33
	ds_read2_b32 v[62:63], v9 offset0:66 offset1:99
	ds_read2_b32 v[64:65], v9 offset0:132 offset1:165
	ds_read2_b32 v[66:67], v9 offset0:198 offset1:231
	ds_read2_b32 v[68:69], v9 offset0:8 offset1:41
	ds_read2_b32 v[70:71], v9 offset0:74 offset1:107
	ds_read2_b32 v[72:73], v9 offset0:140 offset1:173
	ds_read2_b32 v[74:75], v9 offset0:206 offset1:239
	ds_read2_b32 v[76:77], v9 offset0:16 offset1:49
	ds_read2_b32 v[78:79], v9 offset0:82 offset1:115
	ds_read2_b32 v[80:81], v9 offset0:148 offset1:181
	ds_read2_b32 v[82:83], v9 offset0:214 offset1:247
	ds_read2_b32 v[84:85], v9 offset0:24 offset1:57
	ds_read2_b32 v[86:87], v9 offset0:90 offset1:123
	ds_read2_b32 v[88:89], v9 offset0:156 offset1:189
	ds_read2_b32 v[90:91], v9 offset0:222 offset1:255
	s_waitcnt lgkmcnt(12)
	v_mul_f32_e32 v60, v60, v52
	v_mul_f32_e32 v61, v61, v53
	v_mul_f32_e32 v62, v62, v54
	v_mul_f32_e32 v63, v63, v55
	v_mul_f32_e32 v64, v64, v56
	v_mul_f32_e32 v65, v65, v57
	v_mul_f32_e32 v66, v66, v58
	v_mul_f32_e32 v67, v67, v59
	v_cvt_pk_bf16_f32 v92, v60, v61
	v_cvt_pk_bf16_f32 v93, v62, v63
	v_cvt_pk_bf16_f32 v94, v64, v65
	v_cvt_pk_bf16_f32 v95, v66, v67
	global_store_dwordx4 v12, v[92:95], s[64:65]
	s_waitcnt lgkmcnt(8)
	v_mul_f32_e32 v68, v68, v52
	v_mul_f32_e32 v69, v69, v53
	v_mul_f32_e32 v70, v70, v54
	v_mul_f32_e32 v71, v71, v55
	v_mul_f32_e32 v72, v72, v56
	v_mul_f32_e32 v73, v73, v57
	v_mul_f32_e32 v74, v74, v58
	v_mul_f32_e32 v75, v75, v59
	v_cvt_pk_bf16_f32 v96, v68, v69
	v_cvt_pk_bf16_f32 v97, v70, v71
	v_cvt_pk_bf16_f32 v98, v72, v73
	v_cvt_pk_bf16_f32 v99, v74, v75
	global_store_dwordx4 v13, v[96:99], s[64:65]
	s_waitcnt lgkmcnt(4)
	v_mul_f32_e32 v76, v76, v52
	v_mul_f32_e32 v77, v77, v53
	v_mul_f32_e32 v78, v78, v54
	v_mul_f32_e32 v79, v79, v55
	v_mul_f32_e32 v80, v80, v56
	v_mul_f32_e32 v81, v81, v57
	v_mul_f32_e32 v82, v82, v58
	v_mul_f32_e32 v83, v83, v59
	v_cvt_pk_bf16_f32 v100, v76, v77
	v_cvt_pk_bf16_f32 v101, v78, v79
	v_cvt_pk_bf16_f32 v102, v80, v81
	v_cvt_pk_bf16_f32 v103, v82, v83
	global_store_dwordx4 v14, v[100:103], s[64:65]
	s_waitcnt lgkmcnt(0)
	v_mul_f32_e32 v84, v84, v52
	v_mul_f32_e32 v85, v85, v53
	v_mul_f32_e32 v86, v86, v54
	v_mul_f32_e32 v87, v87, v55
	v_mul_f32_e32 v88, v88, v56
	v_mul_f32_e32 v89, v89, v57
	v_mul_f32_e32 v90, v90, v58
	v_mul_f32_e32 v91, v91, v59
	v_cvt_pk_bf16_f32 v104, v84, v85
	v_cvt_pk_bf16_f32 v105, v86, v87
	v_cvt_pk_bf16_f32 v106, v88, v89
	v_cvt_pk_bf16_f32 v107, v90, v91
	global_store_dwordx4 v15, v[104:107], s[64:65]
	s_cmpk_lt_i32 s32, 0x2840
	s_cbranch_scc0 .Lxpwi_fin
; #define LAS __attribute__((address_space(3)))
; __device__ __forceinline__ unsigned cvt_pk_bf16(float lo, float hi) { unsigned r; asm volatile("v_cvt_pk_bf16_f32 %0, %1, %2" : "=v"(r) : "v"(lo), "v"(hi)); return r; }
; __device__ __forceinline__ void xpose_item(const float* src, int ld, bf16_t* dst, int K, int k0, LAS float* scr, int lane, const float* gk) {
;     if (src) {
; #pragma unroll 8
;         for (int i = 0; i < 32; ++i) { const int kk = 2 * i + (lane >> 5); scr[kk * 33 + (lane & 31)] = __builtin_nontemporal_load(src + (size_t)(k0 + kk) * ld + (lane & 31)); }
;     } else {
; #pragma unroll 8
;         for (int i = 0; i < 32; ++i) { const int kk = 2 * i + (lane >> 5); scr[kk * 33 + (lane & 31)] = 0.f; }
;     }
;     const int c = lane & 7;
;     f32x4 g0 = (f32x4){1.f, 1.f, 1.f, 1.f}, g1 = g0;
;     if (gk) { g0 = *(const f32x4*)(gk + k0 + 8 * c); g1 = *(const f32x4*)(gk + k0 + 8 * c + 4); }
;     asm volatile("s_waitcnt lgkmcnt(0)" ::: "memory");
; #pragma unroll
;     for (int j = 0; j < 4; ++j) { const int n = (lane >> 3) + 8 * j; const LAS float* s = scr + (8 * c) * 33 + n;
;         u32x4 o; o.x = cvt_pk_bf16(s[0 * 33] * g0[0], s[1 * 33] * g0[1]); o.y = cvt_pk_bf16(s[2 * 33] * g0[2], s[3 * 33] * g0[3]); o.z = cvt_pk_bf16(s[4 * 33] * g1[0], s[5 * 33] * g1[1]); o.w = cvt_pk_bf16(s[6 * 33] * g1[2], s[7 * 33] * g1[3]);
;         *(u32x4*)(dst + (size_t)n * K + k0 + 8 * c) = o; }
;     asm volatile("s_waitcnt lgkmcnt(0)" ::: "memory");
; }
; __global__ void __launch_bounds__(512) mega(Args a_byval) {
;     ...
;                 it = xpose_all(a.in[15], nullptr, SSD_IN, 2048, SSD_IN, SSD_IN, 0, (bf16_t*)(ws + WS_WB_IN), it, NGW, scr, lane, norm_mix_g + D);
	s_add_i32 s59, s32, 0x400
	s_cmpk_lt_i32 s59, 0x2840
	s_cbranch_scc0 .Lxpwi_dumA
	s_mul_hi_u32 s64, s59, 0xcb8728
	s_mul_i32 s65, s64, 0x142
	s_sub_i32 s65, s59, s65
	s_mul_i32 s66, s64, 0x284000
	s_lshl_b32 s67, s65, 7
	s_add_i32 s66, s66, s67
	s_add_u32 s66, s60, s66
	s_addc_u32 s67, s61, 0
	s_lshl_b32 s64, s64, 8
	s_mov_b32 s65, 0
	v_lshl_add_u64 v[18:19], s[64:65], 0, v[16:17]
	global_load_dwordx4 v[52:55], v[18:19], off
	global_load_dwordx4 v[56:59], v[18:19], off offset:16
	v_mov_b32_e32 v11, v5
	global_load_dword v20, v11, s[66:67] nt
	v_add_u32_e32 v11, 0x14200, v11
	global_load_dword v21, v11, s[66:67] nt
	v_add_u32_e32 v11, 0x14200, v11
	global_load_dword v22, v11, s[66:67] nt
	v_add_u32_e32 v11, 0x14200, v11
	global_load_dword v23, v11, s[66:67] nt
	v_add_u32_e32 v11, 0x14200, v11
	global_load_dword v24, v11, s[66:67] nt
	v_add_u32_e32 v11, 0x14200, v11
	global_load_dword v25, v11, s[66:67] nt
	v_add_u32_e32 v11, 0x14200, v11
	global_load_dword v26, v11, s[66:67] nt
	v_add_u32_e32 v11, 0x14200, v11
	global_load_dword v27, v11, s[66:67] nt
	v_add_u32_e32 v11, 0x14200, v11
	global_load_dword v28, v11, s[66:67] nt
	v_add_u32_e32 v11, 0x14200, v11
	global_load_dword v29, v11, s[66:67] nt
	v_add_u32_e32 v11, 0x14200, v11
	global_load_dword v30, v11, s[66:67] nt
	v_add_u32_e32 v11, 0x14200, v11
	global_load_dword v31, v11, s[66:67] nt
	v_add_u32_e32 v11, 0x14200, v11
	global_load_dword v32, v11, s[66:67] nt
	v_add_u32_e32 v11, 0x14200, v11
	global_load_dword v33, v11, s[66:67] nt
	v_add_u32_e32 v11, 0x14200, v11
	global_load_dword v34, v11, s[66:67] nt
	v_add_u32_e32 v11, 0x14200, v11
	global_load_dword v35, v11, s[66:67] nt
	v_add_u32_e32 v11, 0x14200, v11
	global_load_dword v36, v11, s[66:67] nt
	v_add_u32_e32 v11, 0x14200, v11
	global_load_dword v37, v11, s[66:67] nt
	v_add_u32_e32 v11, 0x14200, v11
	global_load_dword v38, v11, s[66:67] nt
	v_add_u32_e32 v11, 0x14200, v11
	global_load_dword v39, v11, s[66:67] nt
	v_add_u32_e32 v11, 0x14200, v11
	global_load_dword v40, v11, s[66:67] nt
	v_add_u32_e32 v11, 0x14200, v11
	global_load_dword v41, v11, s[66:67] nt
	v_add_u32_e32 v11, 0x14200, v11
	global_load_dword v42, v11, s[66:67] nt
	v_add_u32_e32 v11, 0x14200, v11
	global_load_dword v43, v11, s[66:67] nt
	v_add_u32_e32 v11, 0x14200, v11
	global_load_dword v44, v11, s[66:67] nt
	v_add_u32_e32 v11, 0x14200, v11
	global_load_dword v45, v11, s[66:67] nt
	v_add_u32_e32 v11, 0x14200, v11
	global_load_dword v46, v11, s[66:67] nt
	v_add_u32_e32 v11, 0x14200, v11
	global_load_dword v47, v11, s[66:67] nt
	v_add_u32_e32 v11, 0x14200, v11
	global_load_dword v48, v11, s[66:67] nt
	v_add_u32_e32 v11, 0x14200, v11
	global_load_dword v49, v11, s[66:67] nt
	v_add_u32_e32 v11, 0x14200, v11
	global_load_dword v50, v11, s[66:67] nt
	v_add_u32_e32 v11, 0x14200, v11
	global_load_dword v51, v11, s[66:67] nt
	s_branch .Lxpwi_procB

; #define LAS __attribute__((address_space(3)))
; __device__ __forceinline__ unsigned cvt_pk_bf16(float lo, float hi) { unsigned r; asm volatile("v_cvt_pk_bf16_f32 %0, %1, %2" : "=v"(r) : "v"(lo), "v"(hi)); return r; }
; __device__ __forceinline__ void xpose_item(const float* src, int ld, bf16_t* dst, int K, int k0, LAS float* scr, int lane, const float* gk) {
;     if (src) {
; #pragma unroll 8
;         for (int i = 0; i < 32; ++i) { const int kk = 2 * i + (lane >> 5); scr[kk * 33 + (lane & 31)] = __builtin_nontemporal_load(src + (size_t)(k0 + kk) * ld + (lane & 31)); }
;     } else {
; #pragma unroll 8
;         for (int i = 0; i < 32; ++i) { const int kk = 2 * i + (lane >> 5); scr[kk * 33 + (lane & 31)] = 0.f; }
;     }
;     const int c = lane & 7;
;     f32x4 g0 = (f32x4){1.f, 1.f, 1.f, 1.f}, g1 = g0;
;     if (gk) { g0 = *(const f32x4*)(gk + k0 + 8 * c); g1 = *(const f32x4*)(gk + k0 + 8 * c + 4); }
;     asm volatile("s_waitcnt lgkmcnt(0)" ::: "memory");
; #pragma unroll
;     for (int j = 0; j < 4; ++j) { const int n = (lane >> 3) + 8 * j; const LAS float* s = scr + (8 * c) * 33 + n;
;         u32x4 o; o.x = cvt_pk_bf16(s[0 * 33] * g0[0], s[1 * 33] * g0[1]); o.y = cvt_pk_bf16(s[2 * 33] * g0[2], s[3 * 33] * g0[3]); o.z = cvt_pk_bf16(s[4 * 33] * g1[0], s[5 * 33] * g1[1]); o.w = cvt_pk_bf16(s[6 * 33] * g1[2], s[7 * 33] * g1[3]);
;         *(u32x4*)(dst + (size_t)n * K + k0 + 8 * c) = o; }
;     asm volatile("s_waitcnt lgkmcnt(0)" ::: "memory");
; }
; __global__ void __launch_bounds__(512) mega(Args a_byval) {
;     ...
;                 it = xpose_all(a.in[15], nullptr, SSD_IN, 2048, SSD_IN, SSD_IN, 0, (bf16_t*)(ws + WS_WB_IN), it, NGW, scr, lane, norm_mix_g + D);
.Lxpwi_procB:
	s_mul_hi_u32 s64, s32, 0xcb8728
	s_mul_i32 s65, s64, 0x142
	s_sub_i32 s65, s32, s65
	s_mul_i32 s68, s65, 0x20000
	s_lshl_b32 s64, s64, 7
	s_add_i32 s68, s68, s64
	s_add_u32 s64, s62, s68
	s_addc_u32 s65, s63, 0
	s_waitcnt vmcnt(63)
	ds_write_b32 v6, v108 offset:0
	s_waitcnt vmcnt(62)
	ds_write_b32 v6, v109 offset:264
	s_waitcnt vmcnt(61)
	ds_write_b32 v6, v110 offset:528
	s_waitcnt vmcnt(60)
	ds_write_b32 v6, v111 offset:792
	s_waitcnt vmcnt(59)
	ds_write_b32 v6, v112 offset:1056
	s_waitcnt vmcnt(58)
	ds_write_b32 v6, v113 offset:1320
	s_waitcnt vmcnt(57)
	ds_write_b32 v6, v114 offset:1584
	s_waitcnt vmcnt(56)
	ds_write_b32 v6, v115 offset:1848
	s_waitcnt vmcnt(55)
	ds_write_b32 v6, v116 offset:2112
	s_waitcnt vmcnt(54)
	ds_write_b32 v6, v117 offset:2376
	s_waitcnt vmcnt(53)
	ds_write_b32 v6, v118 offset:2640
	s_waitcnt vmcnt(52)
	ds_write_b32 v6, v119 offset:2904
	s_waitcnt vmcnt(51)
	ds_write_b32 v6, v120 offset:3168
	s_waitcnt vmcnt(50)
	ds_write_b32 v6, v121 offset:3432
	s_waitcnt vmcnt(49)
	ds_write_b32 v6, v122 offset:3696
	s_waitcnt vmcnt(48)
	ds_write_b32 v6, v123 offset:3960
	s_waitcnt vmcnt(47)
	ds_write_b32 v6, v124 offset:4224
	s_waitcnt vmcnt(46)
	ds_write_b32 v6, v125 offset:4488
	s_waitcnt vmcnt(45)
	ds_write_b32 v6, v126 offset:4752
	s_waitcnt vmcnt(44)
	ds_write_b32 v6, v127 offset:5016
	s_waitcnt vmcnt(43)
	ds_write_b32 v6, v128 offset:5280
	s_waitcnt vmcnt(42)
	ds_write_b32 v6, v129 offset:5544
	s_waitcnt vmcnt(41)
	ds_write_b32 v6, v130 offset:5808
	s_waitcnt vmcnt(40)
	ds_write_b32 v6, v131 offset:6072
	s_waitcnt vmcnt(39)
	ds_write_b32 v6, v132 offset:6336
	s_waitcnt vmcnt(38)
	ds_write_b32 v6, v133 offset:6600
	s_waitcnt vmcnt(37)
	ds_write_b32 v6, v134 offset:6864
	s_waitcnt vmcnt(36)
	ds_write_b32 v6, v135 offset:7128
	s_waitcnt vmcnt(35)
	ds_write_b32 v6, v136 offset:7392
	s_waitcnt vmcnt(34)
	ds_write_b32 v6, v137 offset:7656
	s_waitcnt vmcnt(33)
	ds_write_b32 v6, v138 offset:7920
	s_waitcnt vmcnt(32)
	ds_write_b32 v6, v139 offset:8184
	s_waitcnt lgkmcnt(0)
	ds_read2_b32 v[60:61], v9 offset0:0 offset1:33
	ds_read2_b32 v[62:63], v9 offset0:66 offset1:99
	ds_read2_b32 v[64:65], v9 offset0:132 offset1:165
	ds_read2_b32 v[66:67], v9 offset0:198 offset1:231
	ds_read2_b32 v[68:69], v9 offset0:8 offset1:41
	ds_read2_b32 v[70:71], v9 offset0:74 offset1:107
	ds_read2_b32 v[72:73], v9 offset0:140 offset1:173
	ds_read2_b32 v[74:75], v9 offset0:206 offset1:239
	ds_read2_b32 v[76:77], v9 offset0:16 offset1:49
	ds_read2_b32 v[78:79], v9 offset0:82 offset1:115
	ds_read2_b32 v[80:81], v9 offset0:148 offset1:181
	ds_read2_b32 v[82:83], v9 offset0:214 offset1:247
	ds_read2_b32 v[84:85], v9 offset0:24 offset1:57
	ds_read2_b32 v[86:87], v9 offset0:90 offset1:123
	ds_read2_b32 v[88:89], v9 offset0:156 offset1:189
	ds_read2_b32 v[90:91], v9 offset0:222 offset1:255
	s_waitcnt lgkmcnt(12)
	v_mul_f32_e32 v60, v60, v160
	v_mul_f32_e32 v61, v61, v161
	v_mul_f32_e32 v62, v62, v162
	v_mul_f32_e32 v63, v63, v163
	v_mul_f32_e32 v64, v64, v164
	v_mul_f32_e32 v65, v65, v165
	v_mul_f32_e32 v66, v66, v166
	v_mul_f32_e32 v67, v67, v167
	v_cvt_pk_bf16_f32 v92, v60, v61
	v_cvt_pk_bf16_f32 v93, v62, v63
	v_cvt_pk_bf16_f32 v94, v64, v65
	v_cvt_pk_bf16_f32 v95, v66, v67
	global_store_dwordx4 v12, v[92:95], s[64:65]
	s_waitcnt lgkmcnt(8)
	v_mul_f32_e32 v68, v68, v160
	v_mul_f32_e32 v69, v69, v161
	v_mul_f32_e32 v70, v70, v162
	v_mul_f32_e32 v71, v71, v163
	v_mul_f32_e32 v72, v72, v164
	v_mul_f32_e32 v73, v73, v165
	v_mul_f32_e32 v74, v74, v166
	v_mul_f32_e32 v75, v75, v167
	v_cvt_pk_bf16_f32 v96, v68, v69
	v_cvt_pk_bf16_f32 v97, v70, v71
	v_cvt_pk_bf16_f32 v98, v72, v73
	v_cvt_pk_bf16_f32 v99, v74, v75
	global_store_dwordx4 v13, v[96:99], s[64:65]
	s_waitcnt lgkmcnt(4)
	v_mul_f32_e32 v76, v76, v160
	v_mul_f32_e32 v77, v77, v161
	v_mul_f32_e32 v78, v78, v162
	v_mul_f32_e32 v79, v79, v163
	v_mul_f32_e32 v80, v80, v164
	v_mul_f32_e32 v81, v81, v165
	v_mul_f32_e32 v82, v82, v166
	v_mul_f32_e32 v83, v83, v167
	v_cvt_pk_bf16_f32 v100, v76, v77
	v_cvt_pk_bf16_f32 v101, v78, v79
	v_cvt_pk_bf16_f32 v102, v80, v81
	v_cvt_pk_bf16_f32 v103, v82, v83
	global_store_dwordx4 v14, v[100:103], s[64:65]
	s_waitcnt lgkmcnt(0)
	v_mul_f32_e32 v84, v84, v160
	v_mul_f32_e32 v85, v85, v161
	v_mul_f32_e32 v86, v86, v162
	v_mul_f32_e32 v87, v87, v163
	v_mul_f32_e32 v88, v88, v164
	v_mul_f32_e32 v89, v89, v165
	v_mul_f32_e32 v90, v90, v166
	v_mul_f32_e32 v91, v91, v167
	v_cvt_pk_bf16_f32 v104, v84, v85
	v_cvt_pk_bf16_f32 v105, v86, v87
	v_cvt_pk_bf16_f32 v106, v88, v89
	v_cvt_pk_bf16_f32 v107, v90, v91
	global_store_dwordx4 v15, v[104:107], s[64:65]
	s_cmpk_lt_i32 s59, 0x2840
	s_cbranch_scc1 .Lxpwi_loop
	s_branch .Lxpwi_drain

; #define LAS __attribute__((address_space(3)))
; __device__ __forceinline__ unsigned cvt_pk_bf16(float lo, float hi) { unsigned r; asm volatile("v_cvt_pk_bf16_f32 %0, %1, %2" : "=v"(r) : "v"(lo), "v"(hi)); return r; }
; __device__ __forceinline__ void xpose_item(const float* src, int ld, bf16_t* dst, int K, int k0, LAS float* scr, int lane, const float* gk) {
;     if (src) {
; #pragma unroll 8
;         for (int i = 0; i < 32; ++i) { const int kk = 2 * i + (lane >> 5); scr[kk * 33 + (lane & 31)] = __builtin_nontemporal_load(src + (size_t)(k0 + kk) * ld + (lane & 31)); }
;     } else {
; #pragma unroll 8
;         for (int i = 0; i < 32; ++i) { const int kk = 2 * i + (lane >> 5); scr[kk * 33 + (lane & 31)] = 0.f; }
;     }
;     const int c = lane & 7;
;     f32x4 g0 = (f32x4){1.f, 1.f, 1.f, 1.f}, g1 = g0;
;     if (gk) { g0 = *(const f32x4*)(gk + k0 + 8 * c); g1 = *(const f32x4*)(gk + k0 + 8 * c + 4); }
;     asm volatile("s_waitcnt lgkmcnt(0)" ::: "memory");
; #pragma unroll
;     for (int j = 0; j < 4; ++j) { const int n = (lane >> 3) + 8 * j; const LAS float* s = scr + (8 * c) * 33 + n;
;         u32x4 o; o.x = cvt_pk_bf16(s[0 * 33] * g0[0], s[1 * 33] * g0[1]); o.y = cvt_pk_bf16(s[2 * 33] * g0[2], s[3 * 33] * g0[3]); o.z = cvt_pk_bf16(s[4 * 33] * g1[0], s[5 * 33] * g1[1]); o.w = cvt_pk_bf16(s[6 * 33] * g1[2], s[7 * 33] * g1[3]);
;         *(u32x4*)(dst + (size_t)n * K + k0 + 8 * c) = o; }
;     asm volatile("s_waitcnt lgkmcnt(0)" ::: "memory");
; }
; __global__ void __launch_bounds__(512) mega(Args a_byval) {
;     ...
;             it = xpose_all(a.in[25] + (size_t)lyr * D * DFF, nullptr, 2048, DFF, 2048, 2048, 0, (bf16_t*)(ws + (lyr ? WS_W_D : WS_W_D0)), it, NGW, scr, lane);
.Lxpwi_end:
	s_sub_i32 s59, s59, 0x2840
.Lxt7_done:
	s_cmp_lg_u32 s76, 19
	s_cbranch_scc1 .Lxt19_done
	v_readlane_b32 s59, v255, 5
	s_cmpk_lg_i32 s59, 0x100
	s_cbranch_scc1 .Lxt19_done
	s_cmpk_lt_i32 s94, 0x80
	s_cbranch_scc1 .Lxt19_done
	s_sub_i32 s59, s94, 0x80
	s_lshl_b32 s59, s59, 3
	s_add_i32 s59, s59, s95
	s_mul_i32 s64, s95, 0x2100
	v_and_b32_e32 v2, 31, v200
	v_lshrrev_b32_e32 v3, 5, v200
	v_lshlrev_b32_e32 v4, 2, v2
	v_mul_u32_u24_e32 v6, 0x84, v3
	v_add3_u32 v6, v6, v4, s64
	v_and_b32_e32 v7, 7, v200
	v_lshrrev_b32_e32 v8, 3, v200
	v_mul_u32_u24_e32 v9, 0x420, v7
	v_lshl_add_u32 v9, v8, 2, v9
	v_add_u32_e32 v9, s64, v9
	s_cmpk_ge_i32 s59, 0x1600
	s_cbranch_scc1 .Lxpfd_end
	s_load_dwordx2 s[60:61], s[92:93], 0xc8
	s_load_dwordx2 s[62:63], s[92:93], 0xe8
	v_mov_b32_e32 v5, 0x2000
	v_mul_u32_u24_e32 v5, v3, v5
	v_add_u32_e32 v5, v5, v4
	v_mov_b32_e32 v10, 0x2c00
	v_mul_u32_u24_e32 v10, v8, v10
	v_lshl_add_u32 v12, v7, 4, v10
	v_add_u32_e32 v13, 0x16000, v12
	v_add_u32_e32 v14, 0x2c000, v12
	v_add_u32_e32 v15, 0x42000, v12
	s_waitcnt lgkmcnt(0)
	s_add_u32 s60, s60, 0x2c00000
	s_addc_u32 s61, s61, 0
	s_add_u32 s62, s62, 0x6500000
	s_addc_u32 s63, s63, 0
	s_lshr_b32 s64, s59, 6
	s_and_b32 s65, s59, 63
	s_mul_i32 s66, s64, 0x80000
	s_lshl_b32 s67, s65, 7
	s_add_i32 s66, s66, s67
	s_add_u32 s66, s60, s66
	s_addc_u32 s67, s61, 0
	v_mov_b32_e32 v11, v5
	global_load_dword v20, v11, s[66:67] nt
	v_add_u32_e32 v11, 0x4000, v11
	global_load_dword v21, v11, s[66:67] nt
	v_add_u32_e32 v11, 0x4000, v11
	global_load_dword v22, v11, s[66:67] nt
	v_add_u32_e32 v11, 0x4000, v11
	global_load_dword v23, v11, s[66:67] nt
	v_add_u32_e32 v11, 0x4000, v11
	global_load_dword v24, v11, s[66:67] nt
	v_add_u32_e32 v11, 0x4000, v11
	global_load_dword v25, v11, s[66:67] nt
	v_add_u32_e32 v11, 0x4000, v11
	global_load_dword v26, v11, s[66:67] nt
	v_add_u32_e32 v11, 0x4000, v11
	global_load_dword v27, v11, s[66:67] nt
	v_add_u32_e32 v11, 0x4000, v11
	global_load_dword v28, v11, s[66:67] nt
	v_add_u32_e32 v11, 0x4000, v11
	global_load_dword v29, v11, s[66:67] nt
	v_add_u32_e32 v11, 0x4000, v11
	global_load_dword v30, v11, s[66:67] nt
	v_add_u32_e32 v11, 0x4000, v11
	global_load_dword v31, v11, s[66:67] nt
	v_add_u32_e32 v11, 0x4000, v11
	global_load_dword v32, v11, s[66:67] nt
	v_add_u32_e32 v11, 0x4000, v11
	global_load_dword v33, v11, s[66:67] nt
	v_add_u32_e32 v11, 0x4000, v11
	global_load_dword v34, v11, s[66:67] nt
	v_add_u32_e32 v11, 0x4000, v11
	global_load_dword v35, v11, s[66:67] nt
	v_add_u32_e32 v11, 0x4000, v11
	global_load_dword v36, v11, s[66:67] nt
	v_add_u32_e32 v11, 0x4000, v11
	global_load_dword v37, v11, s[66:67] nt
	v_add_u32_e32 v11, 0x4000, v11
	global_load_dword v38, v11, s[66:67] nt
	v_add_u32_e32 v11, 0x4000, v11
	global_load_dword v39, v11, s[66:67] nt
	v_add_u32_e32 v11, 0x4000, v11
	global_load_dword v40, v11, s[66:67] nt
	v_add_u32_e32 v11, 0x4000, v11
	global_load_dword v41, v11, s[66:67] nt
	v_add_u32_e32 v11, 0x4000, v11
	global_load_dword v42, v11, s[66:67] nt
	v_add_u32_e32 v11, 0x4000, v11
	global_load_dword v43, v11, s[66:67] nt
	v_add_u32_e32 v11, 0x4000, v11
	global_load_dword v44, v11, s[66:67] nt
	v_add_u32_e32 v11, 0x4000, v11
	global_load_dword v45, v11, s[66:67] nt
	v_add_u32_e32 v11, 0x4000, v11
	global_load_dword v46, v11, s[66:67] nt
	v_add_u32_e32 v11, 0x4000, v11
	global_load_dword v47, v11, s[66:67] nt
	v_add_u32_e32 v11, 0x4000, v11
	global_load_dword v48, v11, s[66:67] nt
	v_add_u32_e32 v11, 0x4000, v11
	global_load_dword v49, v11, s[66:67] nt
	v_add_u32_e32 v11, 0x4000, v11
	global_load_dword v50, v11, s[66:67] nt
	v_add_u32_e32 v11, 0x4000, v11
	global_load_dword v51, v11, s[66:67] nt

; #define LAS __attribute__((address_space(3)))
; __device__ __forceinline__ void xpose_item(const float* src, int ld, bf16_t* dst, int K, int k0, LAS float* scr, int lane, const float* gk) {
;     if (src) {
; #pragma unroll 8
;         for (int i = 0; i < 32; ++i) { const int kk = 2 * i + (lane >> 5); scr[kk * 33 + (lane & 31)] = __builtin_nontemporal_load(src + (size_t)(k0 + kk) * ld + (lane & 31)); }
;     } else {
; #pragma unroll 8
;         for (int i = 0; i < 32; ++i) { const int kk = 2 * i + (lane >> 5); scr[kk * 33 + (lane & 31)] = 0.f; }
;     }
;     const int c = lane & 7;
;     f32x4 g0 = (f32x4){1.f, 1.f, 1.f, 1.f}, g1 = g0;
;     if (gk) { g0 = *(const f32x4*)(gk + k0 + 8 * c); g1 = *(const f32x4*)(gk + k0 + 8 * c + 4); }
; __global__ void __launch_bounds__(512) mega(Args a_byval) {
;     ...
;             it = xpose_all(a.in[27] + (size_t)lyr * D * D, nullptr, 2048, 2048, 2048, 2048, 0, (bf16_t*)(ws + (lyr ? WS_W_PG1 : WS_W_PG)), it, NGW, scr, lane, norm_ple_g + lyr * D);
.Lxpfd_end:
	s_sub_i32 s59, s59, 0x1600
	s_cmpk_ge_i32 s59, 0x800
	s_cbranch_scc1 .Lxppg_end
	s_load_dwordx2 s[60:61], s[92:93], 0xd8
	s_load_dwordx2 s[62:63], s[92:93], 0xe8
	s_load_dwordx2 s[64:65], s[92:93], 0x20
	v_mov_b32_e32 v5, 0x2000
	v_mul_u32_u24_e32 v5, v3, v5
	v_add_u32_e32 v5, v5, v4
	v_mov_b32_e32 v10, 0x1000
	v_mul_u32_u24_e32 v10, v8, v10
	v_lshl_add_u32 v12, v7, 4, v10
	v_add_u32_e32 v13, 0x8000, v12
	v_add_u32_e32 v14, 0x10000, v12
	v_add_u32_e32 v15, 0x18000, v12
	s_waitcnt lgkmcnt(0)
	s_add_u32 s60, s60, 0x1000000
	s_addc_u32 s61, s61, 0
	s_add_u32 s62, s62, 0x1a00000
	s_addc_u32 s63, s63, 0
	s_add_u32 s64, s64, 0x2000
	s_addc_u32 s65, s65, 0
	v_lshlrev_b32_e32 v16, 5, v7
	v_mov_b32_e32 v17, v0
	v_lshl_add_u64 v[16:17], s[64:65], 0, v[16:17]
	s_lshr_b32 s64, s59, 6
	s_and_b32 s65, s59, 63
	s_mul_i32 s66, s64, 0x80000
	s_lshl_b32 s67, s65, 7
	s_add_i32 s66, s66, s67
	s_add_u32 s66, s60, s66
	s_addc_u32 s67, s61, 0
	s_lshl_b32 s64, s64, 8
	s_mov_b32 s65, 0
	v_lshl_add_u64 v[18:19], s[64:65], 0, v[16:17]
	global_load_dwordx4 v[52:55], v[18:19], off
	global_load_dwordx4 v[56:59], v[18:19], off offset:16
	v_mov_b32_e32 v11, v5
	global_load_dword v20, v11, s[66:67] nt
	v_add_u32_e32 v11, 0x4000, v11
	global_load_dword v21, v11, s[66:67] nt
	v_add_u32_e32 v11, 0x4000, v11
	global_load_dword v22, v11, s[66:67] nt
	v_add_u32_e32 v11, 0x4000, v11
	global_load_dword v23, v11, s[66:67] nt
	v_add_u32_e32 v11, 0x4000, v11
	global_load_dword v24, v11, s[66:67] nt
	v_add_u32_e32 v11, 0x4000, v11
	global_load_dword v25, v11, s[66:67] nt
	v_add_u32_e32 v11, 0x4000, v11
	global_load_dword v26, v11, s[66:67] nt
	v_add_u32_e32 v11, 0x4000, v11
	global_load_dword v27, v11, s[66:67] nt
	v_add_u32_e32 v11, 0x4000, v11
	global_load_dword v28, v11, s[66:67] nt
	v_add_u32_e32 v11, 0x4000, v11
	global_load_dword v29, v11, s[66:67] nt
	v_add_u32_e32 v11, 0x4000, v11
	global_load_dword v30, v11, s[66:67] nt
	v_add_u32_e32 v11, 0x4000, v11
	global_load_dword v31, v11, s[66:67] nt
	v_add_u32_e32 v11, 0x4000, v11
	global_load_dword v32, v11, s[66:67] nt
	v_add_u32_e32 v11, 0x4000, v11
	global_load_dword v33, v11, s[66:67] nt
	v_add_u32_e32 v11, 0x4000, v11
	global_load_dword v34, v11, s[66:67] nt
	v_add_u32_e32 v11, 0x4000, v11
	global_load_dword v35, v11, s[66:67] nt
	v_add_u32_e32 v11, 0x4000, v11
	global_load_dword v36, v11, s[66:67] nt
	v_add_u32_e32 v11, 0x4000, v11
	global_load_dword v37, v11, s[66:67] nt
	v_add_u32_e32 v11, 0x4000, v11
	global_load_dword v38, v11, s[66:67] nt
	v_add_u32_e32 v11, 0x4000, v11
	global_load_dword v39, v11, s[66:67] nt
	v_add_u32_e32 v11, 0x4000, v11
	global_load_dword v40, v11, s[66:67] nt
	v_add_u32_e32 v11, 0x4000, v11
	global_load_dword v41, v11, s[66:67] nt
	v_add_u32_e32 v11, 0x4000, v11
	global_load_dword v42, v11, s[66:67] nt
	v_add_u32_e32 v11, 0x4000, v11
	global_load_dword v43, v11, s[66:67] nt
	v_add_u32_e32 v11, 0x4000, v11
	global_load_dword v44, v11, s[66:67] nt
	v_add_u32_e32 v11, 0x4000, v11
	global_load_dword v45, v11, s[66:67] nt
	v_add_u32_e32 v11, 0x4000, v11
	global_load_dword v46, v11, s[66:67] nt
	v_add_u32_e32 v11, 0x4000, v11
	global_load_dword v47, v11, s[66:67] nt
	v_add_u32_e32 v11, 0x4000, v11
	global_load_dword v48, v11, s[66:67] nt
	v_add_u32_e32 v11, 0x4000, v11
	global_load_dword v49, v11, s[66:67] nt
	v_add_u32_e32 v11, 0x4000, v11
	global_load_dword v50, v11, s[66:67] nt
	v_add_u32_e32 v11, 0x4000, v11
	global_load_dword v51, v11, s[66:67] nt
.Lxppg_loop:
	s_add_i32 s32, s59, 0x400
	s_cmpk_lt_i32 s32, 0x800
	s_cbranch_scc0 .Lxppg_dumB
	s_lshr_b32 s64, s32, 6
	s_and_b32 s65, s32, 63
	s_mul_i32 s66, s64, 0x80000
	s_lshl_b32 s67, s65, 7
	s_add_i32 s66, s66, s67
	s_add_u32 s66, s60, s66
	s_addc_u32 s67, s61, 0
	s_lshl_b32 s64, s64, 8
	s_mov_b32 s65, 0
	v_lshl_add_u64 v[18:19], s[64:65], 0, v[16:17]
	global_load_dwordx4 v[160:163], v[18:19], off
	global_load_dwordx4 v[164:167], v[18:19], off offset:16
	v_mov_b32_e32 v11, v5
	global_load_dword v108, v11, s[66:67] nt
	v_add_u32_e32 v11, 0x4000, v11
	global_load_dword v109, v11, s[66:67] nt
	v_add_u32_e32 v11, 0x4000, v11
	global_load_dword v110, v11, s[66:67] nt
	v_add_u32_e32 v11, 0x4000, v11
	global_load_dword v111, v11, s[66:67] nt
	v_add_u32_e32 v11, 0x4000, v11
	global_load_dword v112, v11, s[66:67] nt
	v_add_u32_e32 v11, 0x4000, v11
	global_load_dword v113, v11, s[66:67] nt
	v_add_u32_e32 v11, 0x4000, v11
	global_load_dword v114, v11, s[66:67] nt
	v_add_u32_e32 v11, 0x4000, v11
	global_load_dword v115, v11, s[66:67] nt
	v_add_u32_e32 v11, 0x4000, v11
	global_load_dword v116, v11, s[66:67] nt
	v_add_u32_e32 v11, 0x4000, v11
	global_load_dword v117, v11, s[66:67] nt
	v_add_u32_e32 v11, 0x4000, v11
	global_load_dword v118, v11, s[66:67] nt
	v_add_u32_e32 v11, 0x4000, v11
	global_load_dword v119, v11, s[66:67] nt
	v_add_u32_e32 v11, 0x4000, v11
	global_load_dword v120, v11, s[66:67] nt
	v_add_u32_e32 v11, 0x4000, v11
	global_load_dword v121, v11, s[66:67] nt
	v_add_u32_e32 v11, 0x4000, v11
	global_load_dword v122, v11, s[66:67] nt
	v_add_u32_e32 v11, 0x4000, v11
	global_load_dword v123, v11, s[66:67] nt
	v_add_u32_e32 v11, 0x4000, v11
	global_load_dword v124, v11, s[66:67] nt
	v_add_u32_e32 v11, 0x4000, v11
	global_load_dword v125, v11, s[66:67] nt
	v_add_u32_e32 v11, 0x4000, v11
	global_load_dword v126, v11, s[66:67] nt
	v_add_u32_e32 v11, 0x4000, v11
	global_load_dword v127, v11, s[66:67] nt
	v_add_u32_e32 v11, 0x4000, v11
	global_load_dword v128, v11, s[66:67] nt
	v_add_u32_e32 v11, 0x4000, v11
	global_load_dword v129, v11, s[66:67] nt
	v_add_u32_e32 v11, 0x4000, v11
	global_load_dword v130, v11, s[66:67] nt
	v_add_u32_e32 v11, 0x4000, v11
	global_load_dword v131, v11, s[66:67] nt
	v_add_u32_e32 v11, 0x4000, v11
	global_load_dword v132, v11, s[66:67] nt
	v_add_u32_e32 v11, 0x4000, v11
	global_load_dword v133, v11, s[66:67] nt
	v_add_u32_e32 v11, 0x4000, v11
	global_load_dword v134, v11, s[66:67] nt
	v_add_u32_e32 v11, 0x4000, v11
	global_load_dword v135, v11, s[66:67] nt
	v_add_u32_e32 v11, 0x4000, v11
	global_load_dword v136, v11, s[66:67] nt
	v_add_u32_e32 v11, 0x4000, v11
	global_load_dword v137, v11, s[66:67] nt
	v_add_u32_e32 v11, 0x4000, v11
	global_load_dword v138, v11, s[66:67] nt
	v_add_u32_e32 v11, 0x4000, v11
	global_load_dword v139, v11, s[66:67] nt
	s_branch .Lxppg_procA

; #define LAS __attribute__((address_space(3)))
; __device__ __forceinline__ unsigned cvt_pk_bf16(float lo, float hi) { unsigned r; asm volatile("v_cvt_pk_bf16_f32 %0, %1, %2" : "=v"(r) : "v"(lo), "v"(hi)); return r; }
; __device__ __forceinline__ void xpose_item(const float* src, int ld, bf16_t* dst, int K, int k0, LAS float* scr, int lane, const float* gk) {
;     ...
;         for (int i = 0; i < 32; ++i) { const int kk = 2 * i + (lane >> 5); scr[kk * 33 + (lane & 31)] = __builtin_nontemporal_load(src + (size_t)(k0 + kk) * ld + (lane & 31)); }
;     } else {
; #pragma unroll 8
;         for (int i = 0; i < 32; ++i) { const int kk = 2 * i + (lane >> 5); scr[kk * 33 + (lane & 31)] = 0.f; }
;     }
;     const int c = lane & 7;
;     f32x4 g0 = (f32x4){1.f, 1.f, 1.f, 1.f}, g1 = g0;
;     if (gk) { g0 = *(const f32x4*)(gk + k0 + 8 * c); g1 = *(const f32x4*)(gk + k0 + 8 * c + 4); }
;     asm volatile("s_waitcnt lgkmcnt(0)" ::: "memory");
; #pragma unroll
;     for (int j = 0; j < 4; ++j) { const int n = (lane >> 3) + 8 * j; const LAS float* s = scr + (8 * c) * 33 + n;
;         u32x4 o; o.x = cvt_pk_bf16(s[0 * 33] * g0[0], s[1 * 33] * g0[1]); o.y = cvt_pk_bf16(s[2 * 33] * g0[2], s[3 * 33] * g0[3]); o.z = cvt_pk_bf16(s[4 * 33] * g1[0], s[5 * 33] * g1[1]); o.w = cvt_pk_bf16(s[6 * 33] * g1[2], s[7 * 33] * g1[3]);
;         *(u32x4*)(dst + (size_t)n * K + k0 + 8 * c) = o; }
.Lxppg_procA:
	s_lshr_b32 s64, s59, 6
	s_and_b32 s65, s59, 63
	s_mul_i32 s68, s65, 0x20000
	s_lshl_b32 s64, s64, 7
	s_add_i32 s68, s68, s64
	s_add_u32 s64, s62, s68
	s_addc_u32 s65, s63, 0
	s_waitcnt vmcnt(63)
	ds_write_b32 v6, v20 offset:0
	s_waitcnt vmcnt(62)
	ds_write_b32 v6, v21 offset:264
	s_waitcnt vmcnt(61)
	ds_write_b32 v6, v22 offset:528
	s_waitcnt vmcnt(60)
	ds_write_b32 v6, v23 offset:792
	s_waitcnt vmcnt(59)
	ds_write_b32 v6, v24 offset:1056
	s_waitcnt vmcnt(58)
	ds_write_b32 v6, v25 offset:1320
	s_waitcnt vmcnt(57)
	ds_write_b32 v6, v26 offset:1584
	s_waitcnt vmcnt(56)
	ds_write_b32 v6, v27 offset:1848
	s_waitcnt vmcnt(55)
	ds_write_b32 v6, v28 offset:2112
	s_waitcnt vmcnt(54)
	ds_write_b32 v6, v29 offset:2376
	s_waitcnt vmcnt(53)
	ds_write_b32 v6, v30 offset:2640
	s_waitcnt vmcnt(52)
	ds_write_b32 v6, v31 offset:2904
	s_waitcnt vmcnt(51)
	ds_write_b32 v6, v32 offset:3168
	s_waitcnt vmcnt(50)
	ds_write_b32 v6, v33 offset:3432
	s_waitcnt vmcnt(49)
	ds_write_b32 v6, v34 offset:3696
	s_waitcnt vmcnt(48)
	ds_write_b32 v6, v35 offset:3960
	s_waitcnt vmcnt(47)
	ds_write_b32 v6, v36 offset:4224
	s_waitcnt vmcnt(46)
	ds_write_b32 v6, v37 offset:4488
	s_waitcnt vmcnt(45)
	ds_write_b32 v6, v38 offset:4752
	s_waitcnt vmcnt(44)
	ds_write_b32 v6, v39 offset:5016
	s_waitcnt vmcnt(43)
	ds_write_b32 v6, v40 offset:5280
	s_waitcnt vmcnt(42)
	ds_write_b32 v6, v41 offset:5544
	s_waitcnt vmcnt(41)
	ds_write_b32 v6, v42 offset:5808
	s_waitcnt vmcnt(40)
	ds_write_b32 v6, v43 offset:6072
	s_waitcnt vmcnt(39)
	ds_write_b32 v6, v44 offset:6336
	s_waitcnt vmcnt(38)
	ds_write_b32 v6, v45 offset:6600
	s_waitcnt vmcnt(37)
	ds_write_b32 v6, v46 offset:6864
	s_waitcnt vmcnt(36)
	ds_write_b32 v6, v47 offset:7128
	s_waitcnt vmcnt(35)
	ds_write_b32 v6, v48 offset:7392
	s_waitcnt vmcnt(34)
	ds_write_b32 v6, v49 offset:7656
	s_waitcnt vmcnt(33)
	ds_write_b32 v6, v50 offset:7920
	s_waitcnt vmcnt(32)
	ds_write_b32 v6, v51 offset:8184
	s_waitcnt lgkmcnt(0)
	ds_read2_b32 v[60:61], v9 offset0:0 offset1:33
	ds_read2_b32 v[62:63], v9 offset0:66 offset1:99
	ds_read2_b32 v[64:65], v9 offset0:132 offset1:165
	ds_read2_b32 v[66:67], v9 offset0:198 offset1:231
	ds_read2_b32 v[68:69], v9 offset0:8 offset1:41
	ds_read2_b32 v[70:71], v9 offset0:74 offset1:107
	ds_read2_b32 v[72:73], v9 offset0:140 offset1:173
	ds_read2_b32 v[74:75], v9 offset0:206 offset1:239
	ds_read2_b32 v[76:77], v9 offset0:16 offset1:49
	ds_read2_b32 v[78:79], v9 offset0:82 offset1:115
	ds_read2_b32 v[80:81], v9 offset0:148 offset1:181
	ds_read2_b32 v[82:83], v9 offset0:214 offset1:247
	ds_read2_b32 v[84:85], v9 offset0:24 offset1:57
	ds_read2_b32 v[86:87], v9 offset0:90 offset1:123
	ds_read2_b32 v[88:89], v9 offset0:156 offset1:189
	ds_read2_b32 v[90:91], v9 offset0:222 offset1:255
	s_waitcnt lgkmcnt(12)
	v_mul_f32_e32 v60, v60, v52
	v_mul_f32_e32 v61, v61, v53
	v_mul_f32_e32 v62, v62, v54
	v_mul_f32_e32 v63, v63, v55
	v_mul_f32_e32 v64, v64, v56
	v_mul_f32_e32 v65, v65, v57
	v_mul_f32_e32 v66, v66, v58
	v_mul_f32_e32 v67, v67, v59
	v_cvt_pk_bf16_f32 v92, v60, v61
	v_cvt_pk_bf16_f32 v93, v62, v63
	v_cvt_pk_bf16_f32 v94, v64, v65
	v_cvt_pk_bf16_f32 v95, v66, v67
	global_store_dwordx4 v12, v[92:95], s[64:65]
	s_waitcnt lgkmcnt(8)
	v_mul_f32_e32 v68, v68, v52
	v_mul_f32_e32 v69, v69, v53
	v_mul_f32_e32 v70, v70, v54
	v_mul_f32_e32 v71, v71, v55
	v_mul_f32_e32 v72, v72, v56
	v_mul_f32_e32 v73, v73, v57
	v_mul_f32_e32 v74, v74, v58
	v_mul_f32_e32 v75, v75, v59
	v_cvt_pk_bf16_f32 v96, v68, v69
	v_cvt_pk_bf16_f32 v97, v70, v71
	v_cvt_pk_bf16_f32 v98, v72, v73
	v_cvt_pk_bf16_f32 v99, v74, v75
	global_store_dwordx4 v13, v[96:99], s[64:65]
	s_waitcnt lgkmcnt(4)
	v_mul_f32_e32 v76, v76, v52
	v_mul_f32_e32 v77, v77, v53
	v_mul_f32_e32 v78, v78, v54
	v_mul_f32_e32 v79, v79, v55
	v_mul_f32_e32 v80, v80, v56
	v_mul_f32_e32 v81, v81, v57
	v_mul_f32_e32 v82, v82, v58
	v_mul_f32_e32 v83, v83, v59
	v_cvt_pk_bf16_f32 v100, v76, v77
	v_cvt_pk_bf16_f32 v101, v78, v79
	v_cvt_pk_bf16_f32 v102, v80, v81
	v_cvt_pk_bf16_f32 v103, v82, v83
	global_store_dwordx4 v14, v[100:103], s[64:65]
	s_waitcnt lgkmcnt(0)
	v_mul_f32_e32 v84, v84, v52
	v_mul_f32_e32 v85, v85, v53
	v_mul_f32_e32 v86, v86, v54
	v_mul_f32_e32 v87, v87, v55
	v_mul_f32_e32 v88, v88, v56
	v_mul_f32_e32 v89, v89, v57
	v_mul_f32_e32 v90, v90, v58
	v_mul_f32_e32 v91, v91, v59
	v_cvt_pk_bf16_f32 v104, v84, v85
	v_cvt_pk_bf16_f32 v105, v86, v87
	v_cvt_pk_bf16_f32 v106, v88, v89
	v_cvt_pk_bf16_f32 v107, v90, v91
	global_store_dwordx4 v15, v[104:107], s[64:65]
	s_cmpk_lt_i32 s32, 0x800
	s_cbranch_scc0 .Lxppg_fin
; #define LAS __attribute__((address_space(3)))
; __device__ __forceinline__ void xpose_item(const float* src, int ld, bf16_t* dst, int K, int k0, LAS float* scr, int lane, const float* gk) {
;     if (src) {
; #pragma unroll 8
;         for (int i = 0; i < 32; ++i) { const int kk = 2 * i + (lane >> 5); scr[kk * 33 + (lane & 31)] = __builtin_nontemporal_load(src + (size_t)(k0 + kk) * ld + (lane & 31)); }
;     } else {
; #pragma unroll 8
;         for (int i = 0; i < 32; ++i) { const int kk = 2 * i + (lane >> 5); scr[kk * 33 + (lane & 31)] = 0.f; }
;     }
;     const int c = lane & 7;
;     f32x4 g0 = (f32x4){1.f, 1.f, 1.f, 1.f}, g1 = g0;
;     if (gk) { g0 = *(const f32x4*)(gk + k0 + 8 * c); g1 = *(const f32x4*)(gk + k0 + 8 * c + 4); }
	s_add_i32 s59, s32, 0x400
	s_cmpk_lt_i32 s59, 0x800
	s_cbranch_scc0 .Lxppg_dumA
	s_lshr_b32 s64, s59, 6
	s_and_b32 s65, s59, 63
	s_mul_i32 s66, s64, 0x80000
	s_lshl_b32 s67, s65, 7
	s_add_i32 s66, s66, s67
	s_add_u32 s66, s60, s66
	s_addc_u32 s67, s61, 0
	s_lshl_b32 s64, s64, 8
	s_mov_b32 s65, 0
	v_lshl_add_u64 v[18:19], s[64:65], 0, v[16:17]
	global_load_dwordx4 v[52:55], v[18:19], off
	global_load_dwordx4 v[56:59], v[18:19], off offset:16
	v_mov_b32_e32 v11, v5
	global_load_dword v20, v11, s[66:67] nt
	v_add_u32_e32 v11, 0x4000, v11
	global_load_dword v21, v11, s[66:67] nt
	v_add_u32_e32 v11, 0x4000, v11
	global_load_dword v22, v11, s[66:67] nt
	v_add_u32_e32 v11, 0x4000, v11
	global_load_dword v23, v11, s[66:67] nt
	v_add_u32_e32 v11, 0x4000, v11
	global_load_dword v24, v11, s[66:67] nt
	v_add_u32_e32 v11, 0x4000, v11
	global_load_dword v25, v11, s[66:67] nt
	v_add_u32_e32 v11, 0x4000, v11
	global_load_dword v26, v11, s[66:67] nt
	v_add_u32_e32 v11, 0x4000, v11
	global_load_dword v27, v11, s[66:67] nt
	v_add_u32_e32 v11, 0x4000, v11
	global_load_dword v28, v11, s[66:67] nt
	v_add_u32_e32 v11, 0x4000, v11
	global_load_dword v29, v11, s[66:67] nt
	v_add_u32_e32 v11, 0x4000, v11
	global_load_dword v30, v11, s[66:67] nt
	v_add_u32_e32 v11, 0x4000, v11
	global_load_dword v31, v11, s[66:67] nt
	v_add_u32_e32 v11, 0x4000, v11
	global_load_dword v32, v11, s[66:67] nt
	v_add_u32_e32 v11, 0x4000, v11
	global_load_dword v33, v11, s[66:67] nt
	v_add_u32_e32 v11, 0x4000, v11
	global_load_dword v34, v11, s[66:67] nt
	v_add_u32_e32 v11, 0x4000, v11
	global_load_dword v35, v11, s[66:67] nt
	v_add_u32_e32 v11, 0x4000, v11
	global_load_dword v36, v11, s[66:67] nt
	v_add_u32_e32 v11, 0x4000, v11
	global_load_dword v37, v11, s[66:67] nt
	v_add_u32_e32 v11, 0x4000, v11
	global_load_dword v38, v11, s[66:67] nt
	v_add_u32_e32 v11, 0x4000, v11
	global_load_dword v39, v11, s[66:67] nt
	v_add_u32_e32 v11, 0x4000, v11
	global_load_dword v40, v11, s[66:67] nt
	v_add_u32_e32 v11, 0x4000, v11
	global_load_dword v41, v11, s[66:67] nt
	v_add_u32_e32 v11, 0x4000, v11
	global_load_dword v42, v11, s[66:67] nt
	v_add_u32_e32 v11, 0x4000, v11
	global_load_dword v43, v11, s[66:67] nt
	v_add_u32_e32 v11, 0x4000, v11
	global_load_dword v44, v11, s[66:67] nt
	v_add_u32_e32 v11, 0x4000, v11
	global_load_dword v45, v11, s[66:67] nt
	v_add_u32_e32 v11, 0x4000, v11
	global_load_dword v46, v11, s[66:67] nt
	v_add_u32_e32 v11, 0x4000, v11
	global_load_dword v47, v11, s[66:67] nt
	v_add_u32_e32 v11, 0x4000, v11
	global_load_dword v48, v11, s[66:67] nt
	v_add_u32_e32 v11, 0x4000, v11
	global_load_dword v49, v11, s[66:67] nt
	v_add_u32_e32 v11, 0x4000, v11
	global_load_dword v50, v11, s[66:67] nt
	v_add_u32_e32 v11, 0x4000, v11
	global_load_dword v51, v11, s[66:67] nt
	s_branch .Lxppg_procB

; #define LAS __attribute__((address_space(3)))
; __device__ __forceinline__ void xpose_item(const float* src, int ld, bf16_t* dst, int K, int k0, LAS float* scr, int lane, const float* gk) {
;     if (src) {
; #pragma unroll 8
;         for (int i = 0; i < 32; ++i) { const int kk = 2 * i + (lane >> 5); scr[kk * 33 + (lane & 31)] = __builtin_nontemporal_load(src + (size_t)(k0 + kk) * ld + (lane & 31)); }
;     } else {
; #pragma unroll 8
;         for (int i = 0; i < 32; ++i) { const int kk = 2 * i + (lane >> 5); scr[kk * 33 + (lane & 31)] = 0.f; }
;     }
;     const int c = lane & 7;
;     f32x4 g0 = (f32x4){1.f, 1.f, 1.f, 1.f}, g1 = g0;
;     if (gk) { g0 = *(const f32x4*)(gk + k0 + 8 * c); g1 = *(const f32x4*)(gk + k0 + 8 * c + 4); }
; __global__ void __launch_bounds__(512) mega(Args a_byval) {
;     ...
;             it = xpose_all(a.in[26] + (size_t)lyr * PLE * D, nullptr, 2048, 256, 2048, 2048, 0, (bf16_t*)(ws + (lyr ? WS_W_PP1 : WS_W_PP)), it, NGW, scr, lane);
.Lxppg_end:
	s_sub_i32 s59, s59, 0x800
	s_cmpk_ge_i32 s59, 0x100
	s_cbranch_scc1 .Lxppp_end
	s_load_dwordx2 s[60:61], s[92:93], 0xd0
	s_load_dwordx2 s[62:63], s[92:93], 0xe8
	v_mov_b32_e32 v5, 0x2000
	v_mul_u32_u24_e32 v5, v3, v5
	v_add_u32_e32 v5, v5, v4
	v_mov_b32_e32 v10, 0x200
	v_mul_u32_u24_e32 v10, v8, v10
	v_lshl_add_u32 v12, v7, 4, v10
	v_add_u32_e32 v13, 0x1000, v12
	v_add_u32_e32 v14, 0x2000, v12
	v_add_u32_e32 v15, 0x3000, v12
	s_waitcnt lgkmcnt(0)
	s_add_u32 s60, s60, 0x200000
	s_addc_u32 s61, s61, 0
	s_add_u32 s62, s62, 0x2200000
	s_addc_u32 s63, s63, 0
	s_lshr_b32 s64, s59, 6
	s_and_b32 s65, s59, 63
	s_mul_i32 s66, s64, 0x80000
	s_lshl_b32 s67, s65, 7
	s_add_i32 s66, s66, s67
	s_add_u32 s66, s60, s66
	s_addc_u32 s67, s61, 0
	v_mov_b32_e32 v11, v5
	global_load_dword v20, v11, s[66:67] nt
	v_add_u32_e32 v11, 0x4000, v11
	global_load_dword v21, v11, s[66:67] nt
	v_add_u32_e32 v11, 0x4000, v11
	global_load_dword v22, v11, s[66:67] nt
	v_add_u32_e32 v11, 0x4000, v11
	global_load_dword v23, v11, s[66:67] nt
	v_add_u32_e32 v11, 0x4000, v11
	global_load_dword v24, v11, s[66:67] nt
	v_add_u32_e32 v11, 0x4000, v11
	global_load_dword v25, v11, s[66:67] nt
	v_add_u32_e32 v11, 0x4000, v11
	global_load_dword v26, v11, s[66:67] nt
	v_add_u32_e32 v11, 0x4000, v11
	global_load_dword v27, v11, s[66:67] nt
	v_add_u32_e32 v11, 0x4000, v11
	global_load_dword v28, v11, s[66:67] nt
	v_add_u32_e32 v11, 0x4000, v11
	global_load_dword v29, v11, s[66:67] nt
	v_add_u32_e32 v11, 0x4000, v11
	global_load_dword v30, v11, s[66:67] nt
	v_add_u32_e32 v11, 0x4000, v11
	global_load_dword v31, v11, s[66:67] nt
	v_add_u32_e32 v11, 0x4000, v11
	global_load_dword v32, v11, s[66:67] nt
	v_add_u32_e32 v11, 0x4000, v11
	global_load_dword v33, v11, s[66:67] nt
	v_add_u32_e32 v11, 0x4000, v11
	global_load_dword v34, v11, s[66:67] nt
	v_add_u32_e32 v11, 0x4000, v11
	global_load_dword v35, v11, s[66:67] nt
	v_add_u32_e32 v11, 0x4000, v11
	global_load_dword v36, v11, s[66:67] nt
	v_add_u32_e32 v11, 0x4000, v11
	global_load_dword v37, v11, s[66:67] nt
	v_add_u32_e32 v11, 0x4000, v11
	global_load_dword v38, v11, s[66:67] nt
	v_add_u32_e32 v11, 0x4000, v11
	global_load_dword v39, v11, s[66:67] nt
	v_add_u32_e32 v11, 0x4000, v11
	global_load_dword v40, v11, s[66:67] nt
	v_add_u32_e32 v11, 0x4000, v11
	global_load_dword v41, v11, s[66:67] nt
	v_add_u32_e32 v11, 0x4000, v11
	global_load_dword v42, v11, s[66:67] nt
	v_add_u32_e32 v11, 0x4000, v11
	global_load_dword v43, v11, s[66:67] nt
	v_add_u32_e32 v11, 0x4000, v11
	global_load_dword v44, v11, s[66:67] nt
	v_add_u32_e32 v11, 0x4000, v11
	global_load_dword v45, v11, s[66:67] nt
	v_add_u32_e32 v11, 0x4000, v11
	global_load_dword v46, v11, s[66:67] nt
	v_add_u32_e32 v11, 0x4000, v11
	global_load_dword v47, v11, s[66:67] nt
	v_add_u32_e32 v11, 0x4000, v11
	global_load_dword v48, v11, s[66:67] nt
	v_add_u32_e32 v11, 0x4000, v11
	global_load_dword v49, v11, s[66:67] nt
	v_add_u32_e32 v11, 0x4000, v11
	global_load_dword v50, v11, s[66:67] nt
	v_add_u32_e32 v11, 0x4000, v11
	global_load_dword v51, v11, s[66:67] nt
.Lxppp_loop:
	s_add_i32 s32, s59, 0x400
	s_cmpk_lt_i32 s32, 0x100
	s_cbranch_scc0 .Lxppp_dumB
	s_lshr_b32 s64, s32, 6
	s_and_b32 s65, s32, 63
	s_mul_i32 s66, s64, 0x80000
	s_lshl_b32 s67, s65, 7
	s_add_i32 s66, s66, s67
	s_add_u32 s66, s60, s66
	s_addc_u32 s67, s61, 0
	v_mov_b32_e32 v11, v5
	global_load_dword v108, v11, s[66:67] nt
	v_add_u32_e32 v11, 0x4000, v11
	global_load_dword v109, v11, s[66:67] nt
	v_add_u32_e32 v11, 0x4000, v11
	global_load_dword v110, v11, s[66:67] nt
	v_add_u32_e32 v11, 0x4000, v11
	global_load_dword v111, v11, s[66:67] nt
	v_add_u32_e32 v11, 0x4000, v11
	global_load_dword v112, v11, s[66:67] nt
	v_add_u32_e32 v11, 0x4000, v11
	global_load_dword v113, v11, s[66:67] nt
	v_add_u32_e32 v11, 0x4000, v11
	global_load_dword v114, v11, s[66:67] nt
	v_add_u32_e32 v11, 0x4000, v11
	global_load_dword v115, v11, s[66:67] nt
	v_add_u32_e32 v11, 0x4000, v11
	global_load_dword v116, v11, s[66:67] nt
	v_add_u32_e32 v11, 0x4000, v11
	global_load_dword v117, v11, s[66:67] nt
	v_add_u32_e32 v11, 0x4000, v11
	global_load_dword v118, v11, s[66:67] nt
	v_add_u32_e32 v11, 0x4000, v11
	global_load_dword v119, v11, s[66:67] nt
	v_add_u32_e32 v11, 0x4000, v11
	global_load_dword v120, v11, s[66:67] nt
	v_add_u32_e32 v11, 0x4000, v11
	global_load_dword v121, v11, s[66:67] nt
	v_add_u32_e32 v11, 0x4000, v11
	global_load_dword v122, v11, s[66:67] nt
	v_add_u32_e32 v11, 0x4000, v11
	global_load_dword v123, v11, s[66:67] nt
	v_add_u32_e32 v11, 0x4000, v11
	global_load_dword v124, v11, s[66:67] nt
	v_add_u32_e32 v11, 0x4000, v11
	global_load_dword v125, v11, s[66:67] nt
	v_add_u32_e32 v11, 0x4000, v11
	global_load_dword v126, v11, s[66:67] nt
	v_add_u32_e32 v11, 0x4000, v11
	global_load_dword v127, v11, s[66:67] nt
	v_add_u32_e32 v11, 0x4000, v11
	global_load_dword v128, v11, s[66:67] nt
	v_add_u32_e32 v11, 0x4000, v11
	global_load_dword v129, v11, s[66:67] nt
	v_add_u32_e32 v11, 0x4000, v11
	global_load_dword v130, v11, s[66:67] nt
	v_add_u32_e32 v11, 0x4000, v11
	global_load_dword v131, v11, s[66:67] nt
	v_add_u32_e32 v11, 0x4000, v11
	global_load_dword v132, v11, s[66:67] nt
	v_add_u32_e32 v11, 0x4000, v11
	global_load_dword v133, v11, s[66:67] nt
	v_add_u32_e32 v11, 0x4000, v11
	global_load_dword v134, v11, s[66:67] nt
	v_add_u32_e32 v11, 0x4000, v11
	global_load_dword v135, v11, s[66:67] nt
	v_add_u32_e32 v11, 0x4000, v11
	global_load_dword v136, v11, s[66:67] nt
	v_add_u32_e32 v11, 0x4000, v11
	global_load_dword v137, v11, s[66:67] nt
	v_add_u32_e32 v11, 0x4000, v11
	global_load_dword v138, v11, s[66:67] nt
	v_add_u32_e32 v11, 0x4000, v11
	global_load_dword v139, v11, s[66:67] nt
	s_branch .Lxppp_procA

; #define LAS __attribute__((address_space(3)))
; __device__ __forceinline__ unsigned cvt_pk_bf16(float lo, float hi) { unsigned r; asm volatile("v_cvt_pk_bf16_f32 %0, %1, %2" : "=v"(r) : "v"(lo), "v"(hi)); return r; }
; __device__ __forceinline__ void xpose_item(const float* src, int ld, bf16_t* dst, int K, int k0, LAS float* scr, int lane, const float* gk) {
;     ...
;         for (int i = 0; i < 32; ++i) { const int kk = 2 * i + (lane >> 5); scr[kk * 33 + (lane & 31)] = __builtin_nontemporal_load(src + (size_t)(k0 + kk) * ld + (lane & 31)); }
;     } else {
; #pragma unroll 8
;         for (int i = 0; i < 32; ++i) { const int kk = 2 * i + (lane >> 5); scr[kk * 33 + (lane & 31)] = 0.f; }
;     }
;     const int c = lane & 7;
;     f32x4 g0 = (f32x4){1.f, 1.f, 1.f, 1.f}, g1 = g0;
;     if (gk) { g0 = *(const f32x4*)(gk + k0 + 8 * c); g1 = *(const f32x4*)(gk + k0 + 8 * c + 4); }
;     asm volatile("s_waitcnt lgkmcnt(0)" ::: "memory");
; #pragma unroll
;     for (int j = 0; j < 4; ++j) { const int n = (lane >> 3) + 8 * j; const LAS float* s = scr + (8 * c) * 33 + n;
;         u32x4 o; o.x = cvt_pk_bf16(s[0 * 33] * g0[0], s[1 * 33] * g0[1]); o.y = cvt_pk_bf16(s[2 * 33] * g0[2], s[3 * 33] * g0[3]); o.z = cvt_pk_bf16(s[4 * 33] * g1[0], s[5 * 33] * g1[1]); o.w = cvt_pk_bf16(s[6 * 33] * g1[2], s[7 * 33] * g1[3]);
;         *(u32x4*)(dst + (size_t)n * K + k0 + 8 * c) = o; }
.Lxppp_procA:
	s_lshr_b32 s64, s59, 6
	s_and_b32 s65, s59, 63
	s_mul_i32 s68, s65, 0x4000
	s_lshl_b32 s64, s64, 7
	s_add_i32 s68, s68, s64
	s_add_u32 s64, s62, s68
	s_addc_u32 s65, s63, 0
	s_waitcnt vmcnt(63)
	ds_write_b32 v6, v20 offset:0
	s_waitcnt vmcnt(62)
	ds_write_b32 v6, v21 offset:264
	s_waitcnt vmcnt(61)
	ds_write_b32 v6, v22 offset:528
	s_waitcnt vmcnt(60)
	ds_write_b32 v6, v23 offset:792
	s_waitcnt vmcnt(59)
	ds_write_b32 v6, v24 offset:1056
	s_waitcnt vmcnt(58)
	ds_write_b32 v6, v25 offset:1320
	s_waitcnt vmcnt(57)
	ds_write_b32 v6, v26 offset:1584
	s_waitcnt vmcnt(56)
	ds_write_b32 v6, v27 offset:1848
	s_waitcnt vmcnt(55)
	ds_write_b32 v6, v28 offset:2112
	s_waitcnt vmcnt(54)
	ds_write_b32 v6, v29 offset:2376
	s_waitcnt vmcnt(53)
	ds_write_b32 v6, v30 offset:2640
	s_waitcnt vmcnt(52)
	ds_write_b32 v6, v31 offset:2904
	s_waitcnt vmcnt(51)
	ds_write_b32 v6, v32 offset:3168
	s_waitcnt vmcnt(50)
	ds_write_b32 v6, v33 offset:3432
	s_waitcnt vmcnt(49)
	ds_write_b32 v6, v34 offset:3696
	s_waitcnt vmcnt(48)
	ds_write_b32 v6, v35 offset:3960
	s_waitcnt vmcnt(47)
	ds_write_b32 v6, v36 offset:4224
	s_waitcnt vmcnt(46)
	ds_write_b32 v6, v37 offset:4488
	s_waitcnt vmcnt(45)
	ds_write_b32 v6, v38 offset:4752
	s_waitcnt vmcnt(44)
	ds_write_b32 v6, v39 offset:5016
	s_waitcnt vmcnt(43)
	ds_write_b32 v6, v40 offset:5280
	s_waitcnt vmcnt(42)
	ds_write_b32 v6, v41 offset:5544
	s_waitcnt vmcnt(41)
	ds_write_b32 v6, v42 offset:5808
	s_waitcnt vmcnt(40)
	ds_write_b32 v6, v43 offset:6072
	s_waitcnt vmcnt(39)
	ds_write_b32 v6, v44 offset:6336
	s_waitcnt vmcnt(38)
	ds_write_b32 v6, v45 offset:6600
	s_waitcnt vmcnt(37)
	ds_write_b32 v6, v46 offset:6864
	s_waitcnt vmcnt(36)
	ds_write_b32 v6, v47 offset:7128
	s_waitcnt vmcnt(35)
	ds_write_b32 v6, v48 offset:7392
	s_waitcnt vmcnt(34)
	ds_write_b32 v6, v49 offset:7656
	s_waitcnt vmcnt(33)
	ds_write_b32 v6, v50 offset:7920
	s_waitcnt vmcnt(32)
	ds_write_b32 v6, v51 offset:8184
	s_waitcnt lgkmcnt(0)
	ds_read2_b32 v[60:61], v9 offset0:0 offset1:33
	ds_read2_b32 v[62:63], v9 offset0:66 offset1:99
	ds_read2_b32 v[64:65], v9 offset0:132 offset1:165
	ds_read2_b32 v[66:67], v9 offset0:198 offset1:231
	ds_read2_b32 v[68:69], v9 offset0:8 offset1:41
	ds_read2_b32 v[70:71], v9 offset0:74 offset1:107
	ds_read2_b32 v[72:73], v9 offset0:140 offset1:173
	ds_read2_b32 v[74:75], v9 offset0:206 offset1:239
	ds_read2_b32 v[76:77], v9 offset0:16 offset1:49
	ds_read2_b32 v[78:79], v9 offset0:82 offset1:115
	ds_read2_b32 v[80:81], v9 offset0:148 offset1:181
	ds_read2_b32 v[82:83], v9 offset0:214 offset1:247
	ds_read2_b32 v[84:85], v9 offset0:24 offset1:57
	ds_read2_b32 v[86:87], v9 offset0:90 offset1:123
	ds_read2_b32 v[88:89], v9 offset0:156 offset1:189
	ds_read2_b32 v[90:91], v9 offset0:222 offset1:255
	s_waitcnt lgkmcnt(12)
	v_cvt_pk_bf16_f32 v92, v60, v61
	v_cvt_pk_bf16_f32 v93, v62, v63
	v_cvt_pk_bf16_f32 v94, v64, v65
	v_cvt_pk_bf16_f32 v95, v66, v67
	global_store_dwordx4 v12, v[92:95], s[64:65]
	s_waitcnt lgkmcnt(8)
	v_cvt_pk_bf16_f32 v96, v68, v69
	v_cvt_pk_bf16_f32 v97, v70, v71
	v_cvt_pk_bf16_f32 v98, v72, v73
	v_cvt_pk_bf16_f32 v99, v74, v75
	global_store_dwordx4 v13, v[96:99], s[64:65]
	s_waitcnt lgkmcnt(4)
	v_cvt_pk_bf16_f32 v100, v76, v77
	v_cvt_pk_bf16_f32 v101, v78, v79
	v_cvt_pk_bf16_f32 v102, v80, v81
	v_cvt_pk_bf16_f32 v103, v82, v83
	global_store_dwordx4 v14, v[100:103], s[64:65]
	s_waitcnt lgkmcnt(0)
	v_cvt_pk_bf16_f32 v104, v84, v85
	v_cvt_pk_bf16_f32 v105, v86, v87
	v_cvt_pk_bf16_f32 v106, v88, v89
	v_cvt_pk_bf16_f32 v107, v90, v91
	global_store_dwordx4 v15, v[104:107], s[64:65]
	s_cmpk_lt_i32 s32, 0x100
	s_cbranch_scc0 .Lxppp_fin
	s_add_i32 s59, s32, 0x400
	s_cmpk_lt_i32 s59, 0x100
	s_cbranch_scc0 .Lxppp_dumA
	s_lshr_b32 s64, s59, 6
	s_and_b32 s65, s59, 63
	s_mul_i32 s66, s64, 0x80000
	s_lshl_b32 s67, s65, 7
	s_add_i32 s66, s66, s67
	s_add_u32 s66, s60, s66
	s_addc_u32 s67, s61, 0
	v_mov_b32_e32 v11, v5
	global_load_dword v20, v11, s[66:67] nt
	v_add_u32_e32 v11, 0x4000, v11
	global_load_dword v21, v11, s[66:67] nt
	v_add_u32_e32 v11, 0x4000, v11
	global_load_dword v22, v11, s[66:67] nt
	v_add_u32_e32 v11, 0x4000, v11
	global_load_dword v23, v11, s[66:67] nt
	v_add_u32_e32 v11, 0x4000, v11
	global_load_dword v24, v11, s[66:67] nt
	v_add_u32_e32 v11, 0x4000, v11
	global_load_dword v25, v11, s[66:67] nt
	v_add_u32_e32 v11, 0x4000, v11
	global_load_dword v26, v11, s[66:67] nt
	v_add_u32_e32 v11, 0x4000, v11
	global_load_dword v27, v11, s[66:67] nt
	v_add_u32_e32 v11, 0x4000, v11
	global_load_dword v28, v11, s[66:67] nt
	v_add_u32_e32 v11, 0x4000, v11
	global_load_dword v29, v11, s[66:67] nt
	v_add_u32_e32 v11, 0x4000, v11
	global_load_dword v30, v11, s[66:67] nt
	v_add_u32_e32 v11, 0x4000, v11
	global_load_dword v31, v11, s[66:67] nt
	v_add_u32_e32 v11, 0x4000, v11
	global_load_dword v32, v11, s[66:67] nt
	v_add_u32_e32 v11, 0x4000, v11
	global_load_dword v33, v11, s[66:67] nt
	v_add_u32_e32 v11, 0x4000, v11
	global_load_dword v34, v11, s[66:67] nt
	v_add_u32_e32 v11, 0x4000, v11
	global_load_dword v35, v11, s[66:67] nt
	v_add_u32_e32 v11, 0x4000, v11
	global_load_dword v36, v11, s[66:67] nt
	v_add_u32_e32 v11, 0x4000, v11
	global_load_dword v37, v11, s[66:67] nt
	v_add_u32_e32 v11, 0x4000, v11
	global_load_dword v38, v11, s[66:67] nt
	v_add_u32_e32 v11, 0x4000, v11
	global_load_dword v39, v11, s[66:67] nt
	v_add_u32_e32 v11, 0x4000, v11
	global_load_dword v40, v11, s[66:67] nt
	v_add_u32_e32 v11, 0x4000, v11
	global_load_dword v41, v11, s[66:67] nt
	v_add_u32_e32 v11, 0x4000, v11
	global_load_dword v42, v11, s[66:67] nt
	v_add_u32_e32 v11, 0x4000, v11
	global_load_dword v43, v11, s[66:67] nt
	v_add_u32_e32 v11, 0x4000, v11
	global_load_dword v44, v11, s[66:67] nt
	v_add_u32_e32 v11, 0x4000, v11
	global_load_dword v45, v11, s[66:67] nt
	v_add_u32_e32 v11, 0x4000, v11
	global_load_dword v46, v11, s[66:67] nt
	v_add_u32_e32 v11, 0x4000, v11
	global_load_dword v47, v11, s[66:67] nt
	v_add_u32_e32 v11, 0x4000, v11
	global_load_dword v48, v11, s[66:67] nt
	v_add_u32_e32 v11, 0x4000, v11
	global_load_dword v49, v11, s[66:67] nt
	v_add_u32_e32 v11, 0x4000, v11
	global_load_dword v50, v11, s[66:67] nt
	v_add_u32_e32 v11, 0x4000, v11
	global_load_dword v51, v11, s[66:67] nt
	s_branch .Lxppp_procB

; #define LAS __attribute__((address_space(3)))
; __device__ __forceinline__ int xpose_all(const float* src, const float* src2, int ld, int K, int ndst, int nsrc, int mode, bf16_t* dst, int it, int NGW, LAS float* scr, int lane, const float* gvec = nullptr) {
;     const int nblk = ndst / 32, nitems = (K / 64) * nblk;
;     for (; it < nitems; it += NGW) {
; __global__ void __launch_bounds__(512) mega(Args a_byval) {
;     ...
;                 it = xpose_all(a.in[15], nullptr, SSD_IN, 2048, SSD_IN, SSD_IN, 0, (bf16_t*)(ws + WS_WB_IN), it, NGW, scr, lane, norm_mix_g + D);
;                 it = xpose_all(a.in[22], nullptr, 2048, 4096, 2048, 2048, 0, (bf16_t*)(ws + WS_WB_OUT), it, NGW, scr, lane);
;             }
;             it = xpose_all(a.in[23] + (size_t)lyr * D * DFF, a.in[24] + (size_t)lyr * D * DFF, DFF, 2048, 2 * DFF, 2 * DFF, 1, (bf16_t*)(ws + (lyr ? WS_W_GU : WS_W_GU0)), it, NGW, scr, lane, norm_ffn_g + lyr * D);
.LBB0_622:
	s_and_b64 vcc, exec, s[0:1]
	s_cbranch_vccz .LBB0_633
	v_readlane_b32 s8, v254, 39
	s_cmpk_gt_i32 s8, 0x283f
	s_mov_b32 s14, s8
	v_readlane_b32 s9, v254, 40
	v_readlane_b32 vcc_lo, v255, 5
	s_cmpk_lg_i32 vcc_lo, 0x100
	s_cbranch_scc1 .Lxs623
	s_addk_i32 s14, 0x2840
	s_branch .LBB0_634
.Lxs623:
	s_cmpk_gt_i32 s8, 0x283f
	s_cbranch_scc1 .LBB0_634
	s_load_dwordx2 s[2:3], s[92:93], 0x78
	s_waitcnt lgkmcnt(0)
	s_load_dwordx8 s[16:23], s[92:93], 0x0
	v_lshlrev_b32_e32 v1, 2, v212
	s_add_u32 s12, s38, 0x8400000
	v_and_b32_e32 v8, 0x7c, v1
	v_and_b32_e32 v1, 7, v212
	v_lshrrev_b32_e32 v5, 3, v211
	s_addc_u32 s13, s39, 0
	v_lshrrev_b32_e32 v2, 5, v211
	v_lshlrev_b32_e32 v6, 5, v1
	v_mov_b32_e32 v7, v0
	v_lshlrev_b32_e32 v3, 2, v5
	v_lshlrev_b32_e32 v12, 11, v5
	v_mov_b32_e32 v5, s26
	v_lshlrev_b32_e32 v10, 3, v1
	s_waitcnt lgkmcnt(0)
	v_lshl_add_u64 v[6:7], s[20:21], 0, v[6:7]
	s_mov_b64 s[0:1], 0x2000
	v_mul_u32_u24_e32 v1, 0x420, v1
	v_or_b32_e32 v14, 0x4000, v12
	v_or_b32_e32 v16, 0x8000, v12
	v_or_b32_e32 v18, 0xc000, v12
	s_cmp_lg_u64 s[2:3], 0
	v_mad_u32_u24 v5, v2, s33, v5
	v_mov_b32_e32 v9, v0
	v_add_u32_e32 v4, s27, v8
	v_lshl_add_u64 v[6:7], v[6:7], 0, s[0:1]
	v_add3_u32 v3, s27, v1, v3
	s_cselect_b64 s[0:1], -1, 0
	v_mov_b32_e32 v1, v2
	v_add3_u32 v5, v5, v8, 0
	v_lshl_add_u64 v[8:9], s[2:3], 0, v[8:9]
	v_or_b32_e32 v36, 14, v2
	v_or_b32_e32 v37, 12, v2
	v_or_b32_e32 v38, 10, v2
	v_or_b32_e32 v39, 8, v2
	v_or_b32_e32 v40, 6, v2
	v_or_b32_e32 v41, 4, v2
	v_or_b32_e32 v42, 2, v2
	v_lshlrev_b32_e32 v10, 1, v10
	v_lshlrev_b32_e32 v12, 1, v12
	v_lshlrev_b32_e32 v14, 1, v14
	v_lshlrev_b32_e32 v16, 1, v16
	v_lshlrev_b32_e32 v18, 1, v18
	s_mov_b32 s14, s8
	s_branch .LBB0_626

; #define LAS __attribute__((address_space(3)))
; __device__ __forceinline__ int xpose_all(const float* src, const float* src2, int ld, int K, int ndst, int nsrc, int mode, bf16_t* dst, int it, int NGW, LAS float* scr, int lane, const float* gvec = nullptr) {
;     const int nblk = ndst / 32, nitems = (K / 64) * nblk;
;     for (; it < nitems; it += NGW) {
;         const int kb = it / nblk, nb = it % nblk, n0 = nb * 32; const float* sp;
;         if (mode == 0) sp = (n0 < nsrc) ? src + n0 : nullptr;
;         else if (mode == 1) { const int unit = n0 >> 8, bj = (n0 >> 7) & 1, cl = n0 & 127; sp = (bj ? src2 : src) + unit * 128 + cl; }
;         else if (mode == 3) { const int pn = n0 >> 8, cl = n0 & 255; sp = src + ((pn >> 2) & 1) * 2048 + ((pn & 3) + 4 * (pn >> 3)) * 256 + cl; }
;         else { const int unit = n0 >> 8, bj = (n0 >> 7) & 1, cl = n0 & 127; sp = (bj ? src2 : src) + (size_t)(unit >> 1) * 65536 + (unit & 1) * 128 + cl; }
;         xpose_item(sp, ld, dst + (size_t)n0 * K, K, kb * 64, scr, lane, gvec);
;     }
;     return it - nitems;
; __global__ void __launch_bounds__(512) mega(Args a_byval) {
;     ...
;             it = xpose_all(a.in[23] + (size_t)lyr * D * DFF, a.in[24] + (size_t)lyr * D * DFF, DFF, 2048, 2 * DFF, 2 * DFF, 1, (bf16_t*)(ws + (lyr ? WS_W_GU : WS_W_GU0)), it, NGW, scr, lane, norm_ffn_g + lyr * D);
;             it = xpose_all(a.in[25] + (size_t)lyr * D * DFF, nullptr, 2048, DFF, 2048, 2048, 0, (bf16_t*)(ws + (lyr ? WS_W_D : WS_W_D0)), it, NGW, scr, lane);
.LBB0_658:
	s_add_i32 s11, s28, 0xffffd400
	v_readlane_b32 vcc_lo, v255, 5
	s_cmpk_lg_i32 vcc_lo, 0x100
	s_cbranch_scc1 .Lxs658
	s_addk_i32 s11, 0x1600
	s_branch .LBB0_669
